# baseline (speedup 1.0000x reference)
; DI void state_finish(AState& st) {
;   const float lt = st.l + __shfl_xor(st.l, 32);
;   const float inv = 1.f / fmaxf(lt, 1e-30f);
; #pragma unroll
;   for (int i = 0; i < 16; ++i) { st.o0[i] *= inv; st.o1[i] *= inv; }
; }
; DI void load_q(bf16x8 (&q)[4], const u16* R, int tq, int qcol) {
;   const int h2 = (TIDX & 63) >> 5;
;   const u16* qp = R + (size_t)tq * LDR + qcol + h2 * 8;
; #pragma unroll
;   for (int ks = 0; ks < 4; ++ks) q[ks] = ld16(qp + ks * 16);
; }
; DI void write_headnorm(const f32x16& o0, const f32x16& o1, const float* __restrict__ gh, u16* obuf, int tq, int colbase) {
;   const int h2 = (TIDX & 63) >> 5;
;   float ss = 0.f;
; #pragma unroll
;   for (int i = 0; i < 16; ++i) ss += o0[i] * o0[i] + o1[i] * o1[i];
;   ss += __shfl_xor(ss, 32);
;   const float rstd = rsqrtf(ss * (1.f / 64.f) + 1e-6f);
; #pragma unroll
;   for (int dt = 0; dt < 2; ++dt)
; #pragma unroll
;     for (int g = 0; g < 4; ++g) {
;       const int d = dt * 32 + 8 * g + 4 * h2;
;       f32x4 gg = *reinterpret_cast<const f32x4*>(gh + d);
;       float v0 = (dt ? o1[4 * g + 0] : o0[4 * g + 0]) * rstd * gg[0];
;       float v1 = (dt ? o1[4 * g + 1] : o0[4 * g + 1]) * rstd * gg[1];
;       float v2 = (dt ? o1[4 * g + 2] : o0[4 * g + 2]) * rstd * gg[2];
;       float v3 = (dt ? o1[4 * g + 3] : o0[4 * g + 3]) * rstd * gg[3];
;       u32x2 pk = {pack2(v0, v1), pack2(v2, v3)};
;       *reinterpret_cast<u32x2*>(obuf + (size_t)tq * DM + colbase + d) = pk;
;     }
.LBB0_677:
	ds_bpermute_b32 v0, v106, v103
	s_waitcnt lgkmcnt(0)
	v_add_f32_e32 v0, v103, v0
	v_max_f32_e32 v0, 0xda24260, v0
	v_div_scale_f32 v34, s[10:11], v0, v0, 1.0
	v_rcp_f32_e32 v35, v34
	v_readlane_b32 s10, v255, 39
	v_readlane_b32 s11, v255, 40
	v_fma_f32 v36, -v34, v35, 1.0
	v_fmac_f32_e32 v35, v36, v35
	v_div_scale_f32 v36, vcc, 1.0, v0, 1.0
	v_mul_f32_e32 v37, v36, v35
	v_fma_f32 v38, -v34, v37, v36
	v_fmac_f32_e32 v37, v38, v35
	v_fma_f32 v34, -v34, v37, v36
	v_div_fmas_f32 v34, v34, v35, v37
	v_div_fixup_f32 v34, v34, v0, 1.0
	v_mov_b32_e32 v0, v159
	v_mul_f32_e32 v36, v28, v34
	v_mul_f32_e32 v37, v29, v34
	v_mul_f32_e32 v28, v12, v34
	v_mul_f32_e32 v29, v13, v34
	v_mul_f32_e32 v30, v30, v34
	v_mul_f32_e32 v31, v31, v34
	v_mul_f32_e32 v12, v28, v28
	v_mul_f32_e32 v13, v29, v29
	v_lshrrev_b32_e32 v0, 3, v0
	v_fma_f32 v38, v36, v36, v12
	v_fma_f32 v39, v37, v37, v13
	v_mul_f32_e32 v12, v14, v34
	v_mul_f32_e32 v13, v15, v34
	v_and_b32_e32 v0, 4, v0
	v_mul_f32_e32 v14, v12, v12
	v_mul_f32_e32 v15, v13, v13
	v_mul_f32_e32 v32, v32, v34
	v_mul_f32_e32 v33, v33, v34
	v_fma_f32 v40, v30, v30, v14
	v_fma_f32 v41, v31, v31, v15
	v_mul_f32_e32 v14, v16, v34
	v_mul_f32_e32 v15, v17, v34
	v_lshlrev_b32_e32 v35, 2, v0
	global_load_dwordx4 v[44:47], v35, s[26:27] offset:2048
	v_mul_f32_e32 v56, v20, v34
	v_mul_f32_e32 v57, v21, v34
	v_mul_f32_e32 v58, v18, v34
	v_mul_f32_e32 v59, v19, v34
	global_load_dwordx4 v[18:21], v35, s[26:27] offset:2080
	v_mul_f32_e32 v16, v14, v14
	v_mul_f32_e32 v17, v15, v15
	v_mul_f32_e32 v62, v24, v34
	v_mul_f32_e32 v63, v25, v34
	v_fma_f32 v42, v32, v32, v16
	v_fma_f32 v43, v33, v33, v17
	v_lshlrev_b64 v[16:17], 11, v[94:95]
	v_lshl_add_u64 v[16:17], s[10:11], 0, v[16:17]
	v_readlane_b32 s10, v255, 24
	v_mul_f32_e32 v64, v22, v34
	v_mul_f32_e32 v65, v23, v34
	global_load_dwordx4 v[22:25], v35, s[26:27] offset:2112
	v_readlane_b32 s11, v255, 25
	s_mov_b32 s11, s3
	v_lshlrev_b32_e32 v0, 1, v0
	v_lshl_add_u64 v[48:49], v[16:17], 0, s[10:11]
	v_lshl_add_u64 v[16:17], v[16:17], 0, v[0:1]
	v_lshl_add_u64 v[60:61], v[16:17], 0, s[10:11]
	v_lshl_add_u64 v[16:17], v[48:49], 0, v[0:1]
	global_load_dwordx4 v[48:51], v35, s[26:27] offset:2144
	global_load_dwordx4 v[52:55], v35, s[26:27] offset:2176
	s_waitcnt vmcnt(6)
	v_mul_f32_e32 v66, v4, v34
	v_mul_f32_e32 v67, v5, v34
	s_waitcnt vmcnt(5)
	v_mul_f32_e32 v70, v2, v34
	v_mul_f32_e32 v71, v3, v34
	v_mul_f32_e32 v4, v66, v66
	v_mul_f32_e32 v5, v67, v67
	v_mul_f32_e32 v2, v70, v70
	v_mul_f32_e32 v3, v71, v71
	v_fma_f32 v68, v56, v56, v4
	v_fma_f32 v69, v57, v57, v5
	v_fma_f32 v72, v58, v58, v2
	v_fma_f32 v73, v59, v59, v3
	global_load_dwordx4 v[2:5], v35, s[26:27] offset:2208
	v_mul_f32_e32 v74, v8, v34
	v_mul_f32_e32 v75, v9, v34
	v_mul_f32_e32 v78, v6, v34
	v_mul_f32_e32 v79, v7, v34
	v_mul_f32_e32 v8, v74, v74
	v_mul_f32_e32 v9, v75, v75
	v_mul_f32_e32 v6, v78, v78
	v_mul_f32_e32 v7, v79, v79
	v_fma_f32 v76, v62, v62, v8
	v_fma_f32 v77, v63, v63, v9
	v_fma_f32 v80, v64, v64, v6
	v_fma_f32 v81, v65, v65, v7
	global_load_dwordx4 v[6:9], v35, s[26:27] offset:2240
	v_add_f32_e32 v0, v72, v73
	v_add_f32_e32 v0, v68, v0
	v_add_f32_e32 v0, v69, v0
	v_add_f32_e32 v0, v80, v0
	v_mul_f32_e32 v10, v10, v34
	v_mul_f32_e32 v11, v11, v34
	v_add_f32_e32 v0, v81, v0
	v_mul_f32_e32 v26, v26, v34
	v_mul_f32_e32 v27, v27, v34
	v_mul_f32_e32 v82, v10, v10
	v_mul_f32_e32 v83, v11, v11
	v_add_f32_e32 v0, v76, v0
	v_fma_f32 v82, v26, v26, v82
	v_fma_f32 v83, v27, v27, v83
	v_add_f32_e32 v0, v77, v0
	v_add_f32_e32 v0, v82, v0
	v_add_f32_e32 v0, v83, v0
	v_add_f32_e32 v0, v38, v0
	v_add_f32_e32 v0, v39, v0
	v_add_f32_e32 v0, v40, v0
	v_add_f32_e32 v0, v41, v0
	v_add_f32_e32 v0, v42, v0
	v_add_f32_e32 v0, v43, v0
	ds_bpermute_b32 v34, v106, v0
	s_mov_b32 s2, s10
	v_writelane_b32 v255, s2, 24
	s_waitcnt lgkmcnt(0)
; DI void write_headnorm(const f32x16& o0, const f32x16& o1, const float* __restrict__ gh, u16* obuf, int tq, int colbase) {
;   const int h2 = (TIDX & 63) >> 5;
;   float ss = 0.f;
; #pragma unroll
;   for (int i = 0; i < 16; ++i) ss += o0[i] * o0[i] + o1[i] * o1[i];
;   ss += __shfl_xor(ss, 32);
;   const float rstd = rsqrtf(ss * (1.f / 64.f) + 1e-6f);
; #pragma unroll
;   for (int dt = 0; dt < 2; ++dt)
; #pragma unroll
;     for (int g = 0; g < 4; ++g) {
;       const int d = dt * 32 + 8 * g + 4 * h2;
;       f32x4 gg = *reinterpret_cast<const f32x4*>(gh + d);
;       float v0 = (dt ? o1[4 * g + 0] : o0[4 * g + 0]) * rstd * gg[0];
;       float v1 = (dt ? o1[4 * g + 1] : o0[4 * g + 1]) * rstd * gg[1];
;       float v2 = (dt ? o1[4 * g + 2] : o0[4 * g + 2]) * rstd * gg[2];
;       float v3 = (dt ? o1[4 * g + 3] : o0[4 * g + 3]) * rstd * gg[3];
;       u32x2 pk = {pack2(v0, v1), pack2(v2, v3)};
;       *reinterpret_cast<u32x2*>(obuf + (size_t)tq * DM + colbase + d) = pk;
;     }
; }
; DI void forget_group(const u16* R, const u16* T, const float* esuf, const float* ctot, const float* gh, u16* obuf, int hh, int g8, float kmax2, char* lds) {
;     ...
;   __syncthreads();
	v_add_f32_e32 v0, v0, v34
	v_fmamk_f32 v0, v0, 0x3c800000, v158
	v_cmp_gt_f32_e32 vcc, s33, v0
	v_mul_f32_e32 v34, 0x4b800000, v0
	v_writelane_b32 v255, s3, 25
	v_cndmask_b32_e32 v0, v0, v34, vcc
	v_rsq_f32_e32 v0, v0
	v_readlane_b32 s2, v254, 58
	s_add_i32 s22, s22, s2
	v_readlane_b32 s2, v254, 59
	v_mul_f32_e32 v34, 0x45800000, v0
	v_cndmask_b32_e32 v0, v0, v34, vcc
	v_mul_f32_e32 v38, v58, v0
	v_mul_f32_e32 v39, v59, v0
	v_mul_f32_e32 v40, v56, v0
	v_mul_f32_e32 v41, v57, v0
	s_add_i32 s21, s21, s2
	s_cmp_gt_i32 s22, 31
	s_waitcnt vmcnt(6)
	v_mul_f32_e32 v38, v44, v38
	v_mul_f32_e32 v39, v45, v39
	v_mul_f32_e32 v40, v46, v40
	v_mul_f32_e32 v41, v47, v41
	v_cvt_pk_bf16_f32 v38, v38, v39
	v_cvt_pk_bf16_f32 v39, v40, v41
	global_store_dwordx2 v[60:61], v[38:39], off
	v_mul_f32_e32 v38, v64, v0
	v_mul_f32_e32 v39, v65, v0
	s_waitcnt vmcnt(6)
	v_mul_f32_e32 v18, v18, v38
	v_mul_f32_e32 v19, v19, v39
	v_mul_f32_e32 v38, v62, v0
	v_mul_f32_e32 v39, v63, v0
	v_cvt_pk_bf16_f32 v18, v18, v19
	v_mul_f32_e32 v20, v20, v38
	v_mul_f32_e32 v21, v21, v39
	s_nop 0
	v_cvt_pk_bf16_f32 v19, v20, v21
	global_store_dwordx2 v[16:17], v[18:19], off offset:16
	v_mul_f32_e32 v18, v26, v0
	v_mul_f32_e32 v19, v27, v0
	v_mul_f32_e32 v20, v36, v0
	v_mul_f32_e32 v21, v37, v0
	s_waitcnt vmcnt(6)
	v_mul_f32_e32 v18, v22, v18
	v_mul_f32_e32 v19, v23, v19
	v_mul_f32_e32 v20, v24, v20
	v_mul_f32_e32 v21, v25, v21
	v_cvt_pk_bf16_f32 v18, v18, v19
	v_cvt_pk_bf16_f32 v19, v20, v21
	global_store_dwordx2 v[16:17], v[18:19], off offset:32
	v_mul_f32_e32 v18, v30, v0
	v_mul_f32_e32 v19, v31, v0
	v_mul_f32_e32 v20, v32, v0
	v_mul_f32_e32 v21, v33, v0
	s_waitcnt vmcnt(6)
	v_mul_f32_e32 v18, v48, v18
	v_mul_f32_e32 v19, v49, v19
	v_mul_f32_e32 v20, v50, v20
	v_mul_f32_e32 v21, v51, v21
	v_cvt_pk_bf16_f32 v18, v18, v19
	v_cvt_pk_bf16_f32 v19, v20, v21
	global_store_dwordx2 v[16:17], v[18:19], off offset:48
	v_mul_f32_e32 v18, v70, v0
	v_mul_f32_e32 v19, v71, v0
	v_mul_f32_e32 v20, v66, v0
	v_mul_f32_e32 v21, v67, v0
	s_waitcnt vmcnt(6)
	v_mul_f32_e32 v18, v52, v18
	v_mul_f32_e32 v19, v53, v19
	v_mul_f32_e32 v20, v54, v20
	v_mul_f32_e32 v21, v55, v21
	v_cvt_pk_bf16_f32 v18, v18, v19
	v_cvt_pk_bf16_f32 v19, v20, v21
	global_store_dwordx2 v[16:17], v[18:19], off offset:64
	v_mul_f32_e32 v18, v78, v0
	v_mul_f32_e32 v19, v79, v0
	s_waitcnt vmcnt(6)
	v_mul_f32_e32 v2, v2, v18
	v_mul_f32_e32 v3, v3, v19
	v_mul_f32_e32 v18, v74, v0
	v_mul_f32_e32 v19, v75, v0
	v_cvt_pk_bf16_f32 v2, v2, v3
	v_mul_f32_e32 v4, v4, v18
	v_mul_f32_e32 v5, v5, v19
	s_nop 0
	v_cvt_pk_bf16_f32 v3, v4, v5
	global_store_dwordx2 v[16:17], v[2:3], off offset:80
	v_mul_f32_e32 v2, v10, v0
	v_mul_f32_e32 v3, v11, v0
	v_mul_f32_e32 v4, v28, v0
	v_mul_f32_e32 v5, v29, v0
	s_waitcnt vmcnt(6)
	v_mul_f32_e32 v2, v6, v2
	v_mul_f32_e32 v3, v7, v3
	v_mul_f32_e32 v4, v8, v4
	v_mul_f32_e32 v5, v9, v5
	v_cvt_pk_bf16_f32 v2, v2, v3
	v_cvt_pk_bf16_f32 v3, v4, v5
	global_store_dwordx2 v[16:17], v[2:3], off offset:96
	global_load_dwordx4 v[2:5], v35, s[26:27] offset:2272
	v_mul_f32_e32 v6, v12, v0
	v_mul_f32_e32 v7, v13, v0
	s_waitcnt vmcnt(0)
	v_mul_f32_e32 v2, v2, v6
	v_mul_f32_e32 v3, v3, v7
	v_mul_f32_e32 v6, v14, v0
	v_mul_f32_e32 v7, v15, v0
	v_cvt_pk_bf16_f32 v2, v2, v3
	v_mul_f32_e32 v4, v4, v6
	v_mul_f32_e32 v5, v5, v7
	s_nop 0
	v_cvt_pk_bf16_f32 v3, v4, v5
	global_store_dwordx2 v[16:17], v[2:3], off offset:112
	s_barrier
	s_cbranch_scc1 .LBB0_716

; #define MFMA32(a, b, c) __builtin_amdgcn_mfma_f32_32x32x16_bf16((a), (b), (c), 0, 0, 0)
; #define NEG_INF (-__builtin_inff())
; DI int pi_row(int r) { return (r & ~12) | ((r & 4) << 1) | ((r & 8) >> 1); }
; DI void forget_group(const u16* R, const u16* T, const float* esuf, const float* ctot, const float* gh, u16* obuf, int hh, int g8, float kmax2, char* lds) {
;     ...
;         const int prow = pi_row(r) + 32 * tl;
; #pragma unroll
;         for (int ks = 0; ks < 4; ++ks) kv.k[ks] = ld16(sK + prow * FG_KROW + ks * 16 + h2 * 8);
; #pragma unroll
;         for (int dt = 0; dt < 2; ++dt)
; #pragma unroll
;           for (int a = 0; a < 2; ++a) kv.v[dt * 2 + a] = ld16(sV + (dt * 32 + r) * F2_VROW + 32 * tl + a * 16 + h2 * 8);
;         kv.cb[0] = *reinterpret_cast<const f32x4*>(sE + 32 * tl + 8 * h2);
;         kv.cb[1] = *reinterpret_cast<const f32x4*>(sE + 32 * tl + 8 * h2 + 4);
;         kv.cb[2] = *reinterpret_cast<const f32x4*>(sE + 32 * tl + 8 * h2 + 16);
;         kv.cb[3] = *reinterpret_cast<const f32x4*>(sE + 32 * tl + 8 * h2 + 20);
;         const float tot = tp[n0 >> 5];
;         f32x16 s;
; #pragma unroll
;         for (int i = 0; i < 16; ++i) s[i] = carry + kv.cb[i >> 2][i & 3];
; #pragma unroll
;         for (int ks = 0; ks < 4; ++ks) s = MFMA32(kv.k[ks], q[ks], s);
;         float sc[16];
; #pragma unroll
;         for (int i = 0; i < 16; ++i) sc[i] = s[i];
;         if (n0 == t0) {
;           const int nbk = n0 + 8 * h2;
; #pragma unroll
;           for (int i = 0; i < 16; ++i) { const int n = nbk + (i & 7) + 16 * (i >> 3); if (n > tq) sc[i] = NEG_INF; }
;         }
;         carry += tot;
;         softmax_step(sc, st, kv);
.LBB0_690:
	s_mul_i32 s2, s13, 0x4900
	s_xor_b64 s[86:87], s[86:87], -1
	v_add_u32_e32 v114, s2, v113
	s_andn2_b64 vcc, exec, s[86:87]
	s_mov_b64 s[86:87], -1
	s_cbranch_vccnz .LBB0_697
	s_cmp_ge_i32 s94, s23
	s_mov_b64 s[90:91], 0
	s_cbranch_scc1 .LBB0_698
	s_addk_i32 s95, 0xe0
	s_ashr_i32 s90, s95, 5
	s_ashr_i32 s91, s90, 31
	s_lshl_b64 s[90:91], s[90:91], 2
	v_readlane_b32 s2, v254, 24
	s_add_u32 s90, s2, s90
	v_readlane_b32 s2, v254, 27
	v_add_u32_e32 v42, v114, v112
	s_addc_u32 s91, s2, s91
	v_add_u32_e32 v0, v114, v110
	ds_read_b128 v[34:37], v42 offset:18640
	ds_read_b128 v[38:41], v42 offset:18624
	ds_read_b128 v[78:81], v42 offset:18576
	ds_read_b128 v[82:85], v42 offset:18560
	ds_read_b128 v[86:89], v0 offset:4608
	global_load_dword v104, v1, s[90:91]
	s_waitcnt lgkmcnt(4)
	v_add_f32_e32 v48, v102, v36
	v_add_f32_e32 v49, v102, v37
	s_waitcnt lgkmcnt(3)
	v_add_f32_e32 v44, v102, v40
	v_add_f32_e32 v45, v102, v41
	s_waitcnt lgkmcnt(2)
	v_add_f32_e32 v40, v102, v80
	v_add_f32_e32 v41, v102, v81
	s_waitcnt lgkmcnt(1)
	v_add_f32_e32 v36, v102, v84
	v_add_f32_e32 v37, v102, v85
	v_add_f32_e32 v46, v102, v34
	v_add_f32_e32 v47, v102, v35
	v_add_f32_e32 v42, v102, v38
	v_add_f32_e32 v43, v102, v39
	v_add_f32_e32 v38, v102, v78
	v_add_f32_e32 v39, v102, v79
	v_add_f32_e32 v34, v102, v82
	v_add_f32_e32 v35, v102, v83
	ds_read_b128 v[78:81], v0 offset:4640
	ds_read_b128 v[82:85], v0 offset:4672
	s_waitcnt lgkmcnt(2)
	v_mfma_f32_32x32x16_bf16 v[34:49], v[86:89], v[50:53], v[34:49]
	ds_read_b128 v[116:119], v0 offset:4704
	v_add_u32_e32 v0, v114, v111
	s_cmp_lg_u32 s16, s10
	s_waitcnt lgkmcnt(2)
	v_mfma_f32_32x32x16_bf16 v[34:49], v[78:81], v[54:57], v[34:49]
	s_waitcnt lgkmcnt(1)
	v_mfma_f32_32x32x16_bf16 v[34:49], v[82:85], v[58:61], v[34:49]
	ds_read_b128 v[90:93], v0 offset:9280
	ds_read_b128 v[86:89], v0 offset:9312
	ds_read_b128 v[82:85], v0 offset:13888
	ds_read_b128 v[78:81], v0 offset:13920
	s_waitcnt lgkmcnt(4)
	v_mfma_f32_32x32x16_bf16 v[34:49], v[116:119], v[62:65], v[34:49]
	s_cbranch_scc1 .Lmy_fg1_nd
	s_nop 10
	v_cndmask_b32_e64 v0, v34, v184, s[50:51]
	v_cndmask_b32_e64 v35, v184, v35, s[52:53]
	v_cndmask_b32_e64 v34, v0, v34, s[52:53]
	v_cndmask_b32_e64 v36, v36, v184, s[54:55]
	v_cndmask_b32_e64 v37, v37, v184, s[56:57]
	v_cndmask_b32_e64 v38, v38, v184, s[58:59]
	v_cndmask_b32_e64 v39, v39, v184, s[60:61]
	v_cndmask_b32_e64 v40, v40, v184, s[62:63]
	v_cndmask_b32_e64 v41, v41, v184, s[64:65]
	v_cndmask_b32_e64 v42, v42, v184, s[66:67]
	v_cndmask_b32_e64 v43, v43, v184, s[68:69]
	v_cndmask_b32_e64 v44, v44, v184, s[70:71]
	v_cndmask_b32_e64 v45, v45, v184, s[72:73]
	v_cndmask_b32_e64 v46, v46, v184, s[74:75]
	v_cndmask_b32_e64 v47, v47, v184, s[76:77]
	v_cndmask_b32_e64 v48, v48, v184, s[78:79]
	v_cndmask_b32_e64 v49, v49, v184, s[80:81]
	v_max3_f32 v0, v34, s35, v35
	v_max3_f32 v0, v0, v36, v37
	v_max3_f32 v0, v0, v38, v39
	v_max3_f32 v0, v0, v40, v41
	v_max3_f32 v0, v0, v42, v43
	v_max3_f32 v0, v0, v44, v45
	v_max3_f32 v0, v0, v46, v47
	v_max3_f32 v0, v0, v48, v49
	ds_bpermute_b32 v115, v106, v0
	s_waitcnt lgkmcnt(0)
	v_max_f32_e32 v120, v0, v115
	s_branch .Lmy_fg1_go

; #define MFMA32(a, b, c) __builtin_amdgcn_mfma_f32_32x32x16_bf16((a), (b), (c), 0, 0, 0)
; #define NEG_INF (-__builtin_inff())
; DI int pi_row(int r) { return (r & ~12) | ((r & 4) << 1) | ((r & 8) >> 1); }
; DI void forget_group(const u16* R, const u16* T, const float* esuf, const float* ctot, const float* gh, u16* obuf, int hh, int g8, float kmax2, char* lds) {
;     ...
;         const int prow = pi_row(r) + 32 * tl;
; #pragma unroll
;         for (int ks = 0; ks < 4; ++ks) kv.k[ks] = ld16(sK + prow * FG_KROW + ks * 16 + h2 * 8);
; #pragma unroll
;         for (int dt = 0; dt < 2; ++dt)
; #pragma unroll
;           for (int a = 0; a < 2; ++a) kv.v[dt * 2 + a] = ld16(sV + (dt * 32 + r) * F2_VROW + 32 * tl + a * 16 + h2 * 8);
;         kv.cb[0] = *reinterpret_cast<const f32x4*>(sE + 32 * tl + 8 * h2);
;         kv.cb[1] = *reinterpret_cast<const f32x4*>(sE + 32 * tl + 8 * h2 + 4);
;         kv.cb[2] = *reinterpret_cast<const f32x4*>(sE + 32 * tl + 8 * h2 + 16);
;         kv.cb[3] = *reinterpret_cast<const f32x4*>(sE + 32 * tl + 8 * h2 + 20);
;         const float tot = tp[n0 >> 5];
;         f32x16 s;
; #pragma unroll
;         for (int i = 0; i < 16; ++i) s[i] = carry + kv.cb[i >> 2][i & 3];
; #pragma unroll
;         for (int ks = 0; ks < 4; ++ks) s = MFMA32(kv.k[ks], q[ks], s);
;         float sc[16];
; #pragma unroll
;         for (int i = 0; i < 16; ++i) sc[i] = s[i];
;         if (n0 == t0) {
;           const int nbk = n0 + 8 * h2;
; #pragma unroll
;           for (int i = 0; i < 16; ++i) { const int n = nbk + (i & 7) + 16 * (i >> 3); if (n > tq) sc[i] = NEG_INF; }
;         }
;         carry += tot;
;         softmax_step(sc, st, kv);
.LBB0_698:
	s_and_b64 vcc, exec, s[90:91]
	s_cbranch_vccnz .LBB0_705
	s_cmp_gt_i32 s94, s23
	s_mov_b64 s[86:87], 0
	s_cbranch_scc1 .LBB0_705
	s_ashr_i32 s86, s94, 5
	s_ashr_i32 s87, s86, 31
	s_lshl_b64 s[86:87], s[86:87], 2
	v_readlane_b32 s2, v254, 24
	s_add_u32 s86, s2, s86
	v_readlane_b32 s2, v254, 27
	v_add_u32_e32 v42, v114, v112
	s_addc_u32 s87, s2, s87
	v_add_u32_e32 v0, v114, v110
	ds_read_b128 v[34:37], v42 offset:18512
	ds_read_b128 v[38:41], v42 offset:18496
	ds_read_b128 v[78:81], v42 offset:18448
	ds_read_b128 v[82:85], v42 offset:18432
	ds_read_b128 v[86:89], v0
	global_load_dword v104, v1, s[86:87]
	s_waitcnt lgkmcnt(4)
	v_add_f32_e32 v48, v102, v36
	v_add_f32_e32 v49, v102, v37
	s_waitcnt lgkmcnt(3)
	v_add_f32_e32 v44, v102, v40
	v_add_f32_e32 v45, v102, v41
	s_waitcnt lgkmcnt(2)
	v_add_f32_e32 v40, v102, v80
	v_add_f32_e32 v41, v102, v81
	s_waitcnt lgkmcnt(1)
	v_add_f32_e32 v36, v102, v84
	v_add_f32_e32 v37, v102, v85
	v_add_f32_e32 v46, v102, v34
	v_add_f32_e32 v47, v102, v35
	v_add_f32_e32 v42, v102, v38
	v_add_f32_e32 v43, v102, v39
	v_add_f32_e32 v38, v102, v78
	v_add_f32_e32 v39, v102, v79
	v_add_f32_e32 v34, v102, v82
	v_add_f32_e32 v35, v102, v83
	ds_read_b128 v[78:81], v0 offset:32
	ds_read_b128 v[116:119], v0 offset:96
	s_waitcnt lgkmcnt(2)
	v_mfma_f32_32x32x16_bf16 v[34:49], v[86:89], v[50:53], v[34:49]
	s_cmp_lg_u32 s12, s10
	s_waitcnt lgkmcnt(1)
	v_mfma_f32_32x32x16_bf16 v[34:49], v[78:81], v[54:57], v[34:49]
	ds_read_b128 v[78:81], v0 offset:64
	v_add_u32_e32 v0, v114, v111
	s_waitcnt lgkmcnt(0)
	v_mfma_f32_32x32x16_bf16 v[34:49], v[78:81], v[58:61], v[34:49]
	ds_read_b128 v[90:93], v0 offset:9216
	ds_read_b128 v[86:89], v0 offset:9248
	ds_read_b128 v[82:85], v0 offset:13824
	ds_read_b128 v[78:81], v0 offset:13856
	v_mfma_f32_32x32x16_bf16 v[34:49], v[116:119], v[62:65], v[34:49]
	s_cbranch_scc1 .Lmy_fg0_nd
	s_nop 10
	v_cndmask_b32_e64 v0, v34, v184, s[50:51]
	v_cndmask_b32_e64 v35, v184, v35, s[52:53]
	v_cndmask_b32_e64 v34, v0, v34, s[52:53]
	v_cndmask_b32_e64 v36, v36, v184, s[54:55]
	v_cndmask_b32_e64 v37, v37, v184, s[56:57]
	v_cndmask_b32_e64 v38, v38, v184, s[58:59]
	v_cndmask_b32_e64 v39, v39, v184, s[60:61]
	v_cndmask_b32_e64 v40, v40, v184, s[62:63]
	v_cndmask_b32_e64 v41, v41, v184, s[64:65]
	v_cndmask_b32_e64 v42, v42, v184, s[66:67]
	v_cndmask_b32_e64 v43, v43, v184, s[68:69]
	v_cndmask_b32_e64 v44, v44, v184, s[70:71]
	v_cndmask_b32_e64 v45, v45, v184, s[72:73]
	v_cndmask_b32_e64 v46, v46, v184, s[74:75]
	v_cndmask_b32_e64 v47, v47, v184, s[76:77]
	v_cndmask_b32_e64 v48, v48, v184, s[78:79]
	v_cndmask_b32_e64 v49, v49, v184, s[80:81]
	v_max3_f32 v0, v34, s35, v35
	v_max3_f32 v0, v0, v36, v37
	v_max3_f32 v0, v0, v38, v39
	v_max3_f32 v0, v0, v40, v41
	v_max3_f32 v0, v0, v42, v43
	v_max3_f32 v0, v0, v44, v45
	v_max3_f32 v0, v0, v46, v47
	v_max3_f32 v0, v0, v48, v49
	ds_bpermute_b32 v114, v106, v0
	s_waitcnt lgkmcnt(0)
	v_max_f32_e32 v120, v0, v114
	s_branch .Lmy_fg0_go

; #define NEG_INF (-__builtin_inff())
; DI void softmax_step(float (&sc)[16], AState& st, const KV& kv) {
;   float mx = NEG_INF;
; #pragma unroll
;   for (int i = 0; i < 16; ++i) mx = fmaxf(mx, sc[i]);
;   mx = fmaxf(mx, __shfl_xor(mx, 32));
;   const float mnew = fmaxf(st.m, mx);
;   const float meff = (mnew == NEG_INF) ? 0.f : mnew;
;   const float alpha = __expf(st.m - meff);
;   float rs = 0.f;
; #pragma unroll
;   for (int i = 0; i < 16; ++i) { sc[i] = __expf(sc[i] - meff); rs += sc[i]; }
;   st.l = st.l * alpha + rs;
;   st.m = mnew;
;   if (__any(alpha != 1.f)) {
; #pragma unroll
;     for (int i = 0; i < 16; ++i) { st.o0[i] *= alpha; st.o1[i] *= alpha; }
; DI void band_tile(const KV& kv, const bf16x8 (&q)[4], AState& st, const Fam& f, int n0, int tq, int wtok, float nslope) {
;   const int h2 = (TIDX & 63) >> 5;
;   f32x16 s = qk_tile(kv, q);
;   float sc[16];
;   const int nb = n0 + 8 * h2;
; #pragma unroll
;   for (int i = 0; i < 16; ++i) {
;     const int n = nb + (i & 7) + 16 * (i >> 3);
;     const int stok = n * f.kstride + f.koff;
;     const int dist = tq - stok;
;     const bool valid = (stok >= 0) && (dist >= 0) && (dist <= wtok);
;     sc[i] = valid ? s[i] + nslope * (float)dist : NEG_INF;
;   }
;   softmax_step(sc, st, kv);
; }
.LBB0_725:
	s_cmp_lt_i32 s23, s30
	s_cselect_b64 s[46:47], -1, 0
	s_cmp_gt_i32 s23, s16
	s_cselect_b64 s[48:49], -1, 0
	s_or_b64 s[46:47], s[46:47], s[48:49]
	s_and_b64 vcc, exec, s[46:47]
	s_cbranch_vccnz .LBB0_729
	s_mul_i32 s14, s22, 0x2680
	s_add_i32 s14, s14, 16
	v_add_u32_e32 v0, s14, v94
	v_add_u32_e32 v6, v0, v96
	ds_read_b128 v[2:5], v6
	ds_read_b128 v[102:105], v6 offset:32
	ds_read_b128 v[106:109], v6 offset:64
	ds_read_b128 v[110:113], v6 offset:96
	v_mov_b32_e32 v14, v159
	v_add_u32_e32 v0, v0, v97
	v_add_u32_e32 v15, s21, v99
	s_waitcnt lgkmcnt(3)
	v_mfma_f32_32x32x16_bf16 v[48:63], v[2:5], v[64:67], 0
	ds_read_b128 v[84:87], v0 offset:4608
	ds_read_b128 v[10:13], v0 offset:4640
	ds_read_b128 v[6:9], v0 offset:7168
	ds_read_b128 v[2:5], v0 offset:7200
	s_nop 0
	v_lshrrev_b32_e32 v0, 2, v14
	v_and_b32_e32 v0, 8, v0
	v_sub_u32_e32 v14, v15, v0
	v_add_co_u32_e32 v15, vcc, s18, v14
	s_waitcnt lgkmcnt(6)
	v_mfma_f32_32x32x16_bf16 v[48:63], v[102:105], v[68:71], v[48:63]
	v_add_u32_e32 v102, 0x1ff, v14
	v_cvt_f32_i32_e32 v15, v15
	v_add_u32_e32 v103, 0x1fe, v14
	v_add_u32_e32 v105, 0x1fc, v14
	v_cvt_f32_i32_e32 v114, v105
	v_add_u32_e32 v104, 0x1fd, v14
	s_waitcnt lgkmcnt(5)
	v_mfma_f32_32x32x16_bf16 v[48:63], v[106:109], v[72:75], v[48:63]
	v_cvt_f32_i32_e32 v107, v102
	v_add_u32_e32 v106, 0x1fb, v14
	v_cvt_f32_i32_e32 v108, v103
	v_cvt_f32_i32_e32 v115, v106
	v_cvt_f32_i32_e32 v109, v104
	s_waitcnt lgkmcnt(4)
	v_mfma_f32_32x32x16_bf16 v[48:63], v[110:113], v[76:79], v[48:63]
	s_nop 11
	v_fma_f32 v15, -v93, v15, v48
	v_fma_f32 v48, -v93, v107, v49
	v_cndmask_b32_e32 v15, v184, v15, vcc
	v_cmp_gt_u32_e32 vcc, s18, v102
	v_fma_f32 v50, -v93, v108, v50
	v_fma_f32 v51, -v93, v109, v51
	v_cndmask_b32_e32 v49, v184, v48, vcc
	v_cmp_gt_u32_e32 vcc, s18, v103
	v_add_u32_e32 v103, 0x1f9, v14
	s_nop 0
	v_cndmask_b32_e32 v48, v184, v50, vcc
	v_fma_f32 v50, -v93, v114, v52
	v_fma_f32 v52, -v93, v115, v53
	v_add_u32_e32 v53, 0x1fa, v14
	v_cvt_f32_i32_e32 v102, v53
	v_cmp_gt_u32_e32 vcc, s18, v104
	v_cvt_f32_i32_e32 v104, v103
	v_fma_f32 v54, -v93, v102, v54
	v_cndmask_b32_e32 v51, v184, v51, vcc
	v_cmp_gt_u32_e32 vcc, s18, v105
	v_add_u32_e32 v102, 0x1f0, v14
	s_nop 0
	v_cndmask_b32_e32 v50, v184, v50, vcc
	v_cmp_gt_u32_e32 vcc, s18, v106
	s_nop 1
	v_cndmask_b32_e32 v52, v184, v52, vcc
	v_cmp_gt_u32_e32 vcc, s18, v53
	s_nop 1
	v_cndmask_b32_e32 v53, v184, v54, vcc
	v_fma_f32 v54, -v93, v104, v55
	v_cmp_gt_u32_e32 vcc, s18, v103
	v_cvt_f32_i32_e32 v104, v102
	v_fma_f32 v56, -v93, v104, v56
	v_cndmask_b32_e32 v55, v184, v54, vcc
	v_add_u32_e32 v54, 0x1ef, v14
	v_cvt_f32_i32_e32 v103, v54
	v_cmp_gt_u32_e32 vcc, s18, v102
	v_add_u32_e32 v102, 0x1ee, v14
	v_fma_f32 v57, -v93, v103, v57
	v_cvt_f32_i32_e32 v103, v102
	v_cndmask_b32_e32 v56, v184, v56, vcc
	v_cmp_gt_u32_e32 vcc, s18, v54
	v_add_u32_e32 v54, 0x1ed, v14
	v_cvt_f32_i32_e32 v104, v54
	v_cndmask_b32_e32 v57, v184, v57, vcc
	v_fma_f32 v58, -v93, v103, v58
	v_cmp_gt_u32_e32 vcc, s18, v102
	v_add_u32_e32 v102, 0x1ec, v14
	v_cvt_f32_i32_e32 v103, v102
	v_cndmask_b32_e32 v58, v184, v58, vcc
	v_cmp_gt_u32_e32 vcc, s18, v54
	v_add_u32_e32 v54, 0x1eb, v14
	v_fma_f32 v59, -v93, v104, v59
	v_cvt_f32_i32_e32 v104, v54
	v_cndmask_b32_e32 v59, v184, v59, vcc
	v_fma_f32 v60, -v93, v103, v60
	v_cmp_gt_u32_e32 vcc, s18, v102
	v_add_u32_e32 v14, 0x1ea, v14
	s_nop 0
	v_cndmask_b32_e32 v102, v184, v60, vcc
	v_fma_f32 v60, -v93, v104, v61
	v_cmp_gt_u32_e32 vcc, s18, v54
	v_cvt_f32_i32_e32 v54, v14
	v_add_u32_e32 v61, s21, v98
	v_sub_u32_e32 v0, v61, v0
	v_cvt_f32_i32_e32 v61, v0
	v_cndmask_b32_e32 v60, v184, v60, vcc
	v_fma_f32 v54, -v93, v54, v62
	v_cmp_gt_u32_e32 vcc, s18, v14
	v_fma_f32 v14, -v93, v61, v63
	s_nop 0
	v_cndmask_b32_e32 v62, v184, v54, vcc
	v_cmp_gt_u32_e32 vcc, s18, v0
	v_max3_f32 v0, v15, s35, v49
	v_max3_f32 v0, v0, v48, v51
	v_cndmask_b32_e32 v54, v184, v14, vcc
	v_max3_f32 v0, v0, v50, v52
	v_mbcnt_hi_u32_b32 v14, -1, v180
	v_max3_f32 v0, v0, v53, v55
	v_and_b32_e32 v63, 64, v14
	v_max3_f32 v0, v0, v56, v57
	v_xor_b32_e32 v61, 32, v14
	v_add_u32_e32 v63, 64, v63
	v_max3_f32 v0, v0, v58, v59
	v_cmp_lt_i32_e32 vcc, v61, v63
	v_max3_f32 v0, v0, v102, v60
	v_max3_f32 v0, v0, v62, v54
	v_cndmask_b32_e32 v14, v14, v61, vcc
	v_lshlrev_b32_e32 v14, 2, v14
	ds_bpermute_b32 v14, v14, v0
	s_waitcnt lgkmcnt(0)
	v_max3_f32 v14, v101, v0, v14
	v_cmp_neq_f32_e32 vcc, s35, v14
	s_nop 1
	v_cndmask_b32_e32 v61, 0, v14, vcc
	v_sub_f32_e32 v0, v101, v61
	v_mul_f32_e32 v0, 0x3fb8aa3b, v0
	v_exp_f32_e32 v0, v0
	s_nop 0
	v_cmp_neq_f32_e32 vcc, 1.0, v0
	s_cbranch_vccz .LBB0_728
	v_mul_f32_e32 v30, v30, v0
	v_mul_f32_e32 v31, v31, v0
	v_mul_f32_e32 v28, v28, v0
	v_mul_f32_e32 v29, v29, v0
	v_mul_f32_e32 v26, v26, v0
	v_mul_f32_e32 v27, v27, v0
	v_mul_f32_e32 v24, v24, v0
	v_mul_f32_e32 v25, v25, v0
	v_mul_f32_e32 v22, v22, v0
	v_mul_f32_e32 v23, v23, v0
	v_mul_f32_e32 v20, v20, v0
	v_mul_f32_e32 v21, v21, v0
	v_mul_f32_e32 v18, v18, v0
	v_mul_f32_e32 v19, v19, v0
	v_mul_f32_e32 v16, v16, v0
	v_mul_f32_e32 v17, v17, v0
	v_mul_f32_e32 v46, v46, v0
	v_mul_f32_e32 v47, v47, v0
	v_mul_f32_e32 v44, v44, v0
	v_mul_f32_e32 v45, v45, v0
	v_mul_f32_e32 v42, v42, v0
	v_mul_f32_e32 v43, v43, v0
	v_mul_f32_e32 v40, v40, v0
	v_mul_f32_e32 v41, v41, v0
	v_mul_f32_e32 v38, v38, v0
	v_mul_f32_e32 v39, v39, v0
	v_mul_f32_e32 v36, v36, v0
	v_mul_f32_e32 v37, v37, v0
	v_mul_f32_e32 v34, v34, v0
	v_mul_f32_e32 v35, v35, v0
	v_mul_f32_e32 v32, v32, v0
	v_mul_f32_e32 v33, v33, v0

; DI void state_finish(AState& st) {
;   const float lt = st.l + __shfl_xor(st.l, 32);
;   const float inv = 1.f / fmaxf(lt, 1e-30f);
; #pragma unroll
;   for (int i = 0; i < 16; ++i) { st.o0[i] *= inv; st.o1[i] *= inv; }
; }
; DI void win_group(const u16* R, const u16* T, float* Ow, int qpair, char* lds) {
;     ...
;   state_finish(st);
;   float* orow = Ow + (size_t)tq * 256 + hh * 64;
; #pragma unroll
;   for (int g = 0; g < 4; ++g) {
;     f32x4 a = {st.o0[4 * g], st.o0[4 * g + 1], st.o0[4 * g + 2], st.o0[4 * g + 3]};
;     f32x4 b = {st.o1[4 * g], st.o1[4 * g + 1], st.o1[4 * g + 2], st.o1[4 * g + 3]};
;     *reinterpret_cast<f32x4*>(orow + 8 * g + 4 * h2) = a;
;     *reinterpret_cast<f32x4*>(orow + 32 + 8 * g + 4 * h2) = b;
;   }
.LBB0_733:
	s_andn2_b64 vcc, exec, s[26:27]
	s_cbranch_vccnz .LBB0_723
	v_mbcnt_hi_u32_b32 v0, -1, v180
	v_and_b32_e32 v3, 64, v0
	v_xor_b32_e32 v2, 32, v0
	v_add_u32_e32 v3, 64, v3
	v_cmp_lt_i32_e32 vcc, v2, v3
	s_lshl_b32 s2, s2, 2
	v_mov_b32_e32 v95, v1
	v_cndmask_b32_e32 v0, v0, v2, vcc
	v_lshlrev_b32_e32 v0, 2, v0
	ds_bpermute_b32 v0, v0, v100
	s_waitcnt lgkmcnt(0)
	v_add_f32_e32 v0, v100, v0
	v_max_f32_e32 v0, 0xda24260, v0
	v_div_scale_f32 v2, s[22:23], v0, v0, 1.0
	v_rcp_f32_e32 v3, v2
	v_div_scale_f32 v4, vcc, 1.0, v0, 1.0
	v_readlane_b32 s22, v252, 60
	v_fma_f32 v5, -v2, v3, 1.0
	v_fmac_f32_e32 v3, v5, v3
	v_mul_f32_e32 v5, v4, v3
	v_fma_f32 v6, -v2, v5, v4
	v_fmac_f32_e32 v5, v6, v3
	v_fma_f32 v2, -v2, v5, v4
	v_div_fmas_f32 v2, v2, v3, v5
	v_div_fixup_f32 v0, v2, v0, 1.0
	v_mul_f32_e32 v10, v20, v0
	v_mul_f32_e32 v11, v21, v0
	v_mul_f32_e32 v20, v26, v0
	v_mul_f32_e32 v21, v27, v0
	v_mul_f32_e32 v26, v28, v0
	v_mul_f32_e32 v27, v29, v0
	v_mul_f32_e32 v28, v30, v0
	v_mul_f32_e32 v29, v31, v0
	v_lshlrev_b64 v[30:31], 10, v[88:89]
	v_readlane_b32 s23, v252, 61
	v_mul_f32_e32 v2, v16, v0
	v_mul_f32_e32 v3, v17, v0
	v_mul_f32_e32 v6, v32, v0
	v_mul_f32_e32 v7, v33, v0
	v_lshl_add_u64 v[30:31], s[22:23], 0, v[30:31]
	v_lshl_add_u64 v[30:31], v[30:31], 0, s[2:3]
	v_readlane_b32 s22, v252, 0
	v_readlane_b32 s2, v254, 62
	s_add_i32 s12, s12, s22
	s_add_i32 s10, s10, s2
	s_add_i32 s11, s11, s2
	v_mul_f32_e32 v4, v18, v0
	v_mul_f32_e32 v5, v19, v0
	v_mul_f32_e32 v8, v34, v0
	v_mul_f32_e32 v9, v35, v0
	v_mul_f32_e32 v32, v44, v0
	v_mul_f32_e32 v33, v45, v0
	v_mul_f32_e32 v34, v46, v0
	v_mul_f32_e32 v35, v47, v0
	v_lshl_add_u64 v[30:31], v[30:31], 0, v[94:95]
	s_cmpk_gt_i32 s12, 0xff
	v_mul_f32_e32 v14, v36, v0
	v_mul_f32_e32 v15, v37, v0
	v_mul_f32_e32 v12, v22, v0
	v_mul_f32_e32 v13, v23, v0
	v_mul_f32_e32 v16, v38, v0
	v_mul_f32_e32 v17, v39, v0
	v_mul_f32_e32 v18, v24, v0
	v_mul_f32_e32 v19, v25, v0
	v_mul_f32_e32 v22, v40, v0
	v_mul_f32_e32 v23, v41, v0
	v_mul_f32_e32 v24, v42, v0
	v_mul_f32_e32 v25, v43, v0
	global_store_dwordx4 v[30:31], v[2:5], off
	global_store_dwordx4 v[30:31], v[6:9], off offset:128
	global_store_dwordx4 v[30:31], v[10:13], off offset:32
	global_store_dwordx4 v[30:31], v[14:17], off offset:160
	global_store_dwordx4 v[30:31], v[18:21], off offset:64
	global_store_dwordx4 v[30:31], v[22:25], off offset:192
	global_store_dwordx4 v[30:31], v[26:29], off offset:96
	v_readlane_b32 s23, v252, 1
	global_store_dwordx4 v[30:31], v[32:35], off offset:224
	s_cbranch_scc0 .LBB0_718

; DI void state_finish(AState& st) {
;   const float lt = st.l + __shfl_xor(st.l, 32);
;   const float inv = 1.f / fmaxf(lt, 1e-30f);
; #pragma unroll
;   for (int i = 0; i < 16; ++i) { st.o0[i] *= inv; st.o1[i] *= inv; }
; }
; DI void load_q(bf16x8 (&q)[4], const u16* R, int tq, int qcol) {
;   const int h2 = (TIDX & 63) >> 5;
;   const u16* qp = R + (size_t)tq * LDR + qcol + h2 * 8;
; #pragma unroll
;   for (int ks = 0; ks < 4; ++ks) q[ks] = ld16(qp + ks * 16);
; }
; DI void write_headnorm(const f32x16& o0, const f32x16& o1, const float* __restrict__ gh, u16* obuf, int tq, int colbase) {
;   const int h2 = (TIDX & 63) >> 5;
;   float ss = 0.f;
; #pragma unroll
;   for (int i = 0; i < 16; ++i) ss += o0[i] * o0[i] + o1[i] * o1[i];
;   ss += __shfl_xor(ss, 32);
;   const float rstd = rsqrtf(ss * (1.f / 64.f) + 1e-6f);
; #pragma unroll
;   for (int dt = 0; dt < 2; ++dt)
; #pragma unroll
;     for (int g = 0; g < 4; ++g) {
;       const int d = dt * 32 + 8 * g + 4 * h2;
;       f32x4 gg = *reinterpret_cast<const f32x4*>(gh + d);
;       float v0 = (dt ? o1[4 * g + 0] : o0[4 * g + 0]) * rstd * gg[0];
;       float v1 = (dt ? o1[4 * g + 1] : o0[4 * g + 1]) * rstd * gg[1];
;       float v2 = (dt ? o1[4 * g + 2] : o0[4 * g + 2]) * rstd * gg[2];
;       float v3 = (dt ? o1[4 * g + 3] : o0[4 * g + 3]) * rstd * gg[3];
;       u32x2 pk = {pack2(v0, v1), pack2(v2, v3)};
;       *reinterpret_cast<u32x2*>(obuf + (size_t)tq * DM + colbase + d) = pk;
;     }
; }
; DI void dil_item(const u16* R, const u16* T, const float* gh, u16* obuf, int wi) {
;     ...
;   state_finish(st);
;   write_headnorm(st.o0, st.o1, gh + (4 + hh) * 64, obuf, tq, (4 + hh) * 64);
.LBB0_737:
	s_waitcnt vmcnt(7)
	v_cmp_lt_i32_e32 vcc, v80, v81
	s_lshl_b32 s2, s50, 2
	s_add_u32 s30, s21, s2
	v_cndmask_b32_e32 v0, v79, v80, vcc
	s_waitcnt vmcnt(3)
	v_lshlrev_b32_e32 v82, 2, v0
	ds_bpermute_b32 v0, v82, v66
	s_addc_u32 s31, s22, 0
	s_lshl_b32 s2, s50, 1
	s_waitcnt lgkmcnt(0)
	v_add_f32_e32 v0, v66, v0
	v_max_f32_e32 v0, 0xda24260, v0
	v_div_scale_f32 v2, s[10:11], v0, v0, 1.0
	v_rcp_f32_e32 v3, v2
	v_readlane_b32 s10, v255, 39
	v_readlane_b32 s11, v255, 40
	v_fma_f32 v4, -v2, v3, 1.0
	v_fmac_f32_e32 v3, v4, v3
	v_div_scale_f32 v4, vcc, 1.0, v0, 1.0
	v_mul_f32_e32 v5, v4, v3
	v_fma_f32 v6, -v2, v5, v4
	v_fmac_f32_e32 v5, v6, v3
	v_fma_f32 v2, -v2, v5, v4
	v_div_fmas_f32 v2, v2, v3, v5
	v_div_fixup_f32 v2, v2, v0, 1.0
	v_mov_b32_e32 v0, v159
	v_mul_f32_e32 v4, v44, v2
	v_mul_f32_e32 v5, v45, v2
	v_mul_f32_e32 v14, v60, v2
	v_mul_f32_e32 v15, v61, v2
	v_mul_f32_e32 v6, v4, v4
	v_mul_f32_e32 v7, v5, v5
	v_lshrrev_b32_e32 v0, 3, v0
	v_fma_f32 v18, v14, v14, v6
	v_fma_f32 v19, v15, v15, v7
	v_mul_f32_e32 v6, v46, v2
	v_mul_f32_e32 v7, v47, v2
	v_mul_f32_e32 v12, v62, v2
	v_mul_f32_e32 v13, v63, v2
	v_mul_f32_e32 v8, v6, v6
	v_mul_f32_e32 v9, v7, v7
	v_and_b32_e32 v0, 4, v0
	v_fma_f32 v20, v12, v12, v8
	v_fma_f32 v21, v13, v13, v9
	v_mul_f32_e32 v16, v64, v2
	v_mul_f32_e32 v17, v65, v2
	v_mul_f32_e32 v8, v48, v2
	v_mul_f32_e32 v9, v49, v2
	v_lshlrev_b32_e32 v3, 2, v0
	global_load_dwordx4 v[24:27], v3, s[30:31] offset:1024
	global_load_dwordx4 v[28:31], v3, s[30:31] offset:1056
	global_load_dwordx4 v[44:47], v3, s[30:31] offset:1088
	v_mul_f32_e32 v60, v52, v2
	v_mul_f32_e32 v61, v53, v2
	v_mul_f32_e32 v62, v50, v2
	v_mul_f32_e32 v63, v51, v2
	v_mul_f32_e32 v64, v54, v2
	v_mul_f32_e32 v65, v55, v2
	global_load_dwordx4 v[48:51], v3, s[30:31] offset:1120
	global_load_dwordx4 v[52:55], v3, s[30:31] offset:1152
	v_mul_f32_e32 v66, v36, v2
	v_mul_f32_e32 v67, v37, v2
	v_mul_f32_e32 v70, v34, v2
	v_mul_f32_e32 v71, v35, v2
	v_mul_f32_e32 v32, v66, v66
	v_mul_f32_e32 v33, v67, v67
	v_mul_f32_e32 v40, v40, v2
	v_mul_f32_e32 v41, v41, v2
	v_fma_f32 v68, v60, v60, v32
	v_fma_f32 v69, v61, v61, v33
	v_mul_f32_e32 v32, v70, v70
	v_mul_f32_e32 v33, v71, v71
	v_mul_f32_e32 v56, v56, v2
	v_mul_f32_e32 v57, v57, v2
	v_fma_f32 v72, v62, v62, v32
	v_fma_f32 v73, v63, v63, v33
	global_load_dwordx4 v[32:35], v3, s[30:31] offset:1184
	v_mul_f32_e32 v36, v40, v40
	v_mul_f32_e32 v37, v41, v41
	v_mul_f32_e32 v76, v38, v2
	v_mul_f32_e32 v77, v39, v2
	v_fma_f32 v74, v56, v56, v36
	v_fma_f32 v75, v57, v57, v37
	v_mul_f32_e32 v36, v76, v76
	v_mul_f32_e32 v37, v77, v77
	v_mul_f32_e32 v10, v8, v8
	v_mul_f32_e32 v11, v9, v9
	v_fma_f32 v78, v64, v64, v36
	v_fma_f32 v79, v65, v65, v37
	global_load_dwordx4 v[36:39], v3, s[30:31] offset:1216
	v_fma_f32 v22, v16, v16, v10
	v_fma_f32 v23, v17, v17, v11
	v_lshlrev_b64 v[10:11], 11, v[160:161]
	v_lshl_add_u64 v[10:11], s[10:11], 0, v[10:11]
	v_lshl_add_u64 v[10:11], v[10:11], 0, s[2:3]
	v_lshlrev_b32_e32 v0, 1, v0
	v_lshl_add_u64 v[10:11], v[10:11], 0, v[0:1]
	v_add_f32_e32 v0, v72, v73
	v_add_f32_e32 v0, v68, v0
	v_add_f32_e32 v0, v69, v0
	v_add_f32_e32 v0, v78, v0
	v_mul_f32_e32 v42, v42, v2
	v_mul_f32_e32 v43, v43, v2
	v_add_f32_e32 v0, v79, v0
	v_mul_f32_e32 v58, v58, v2
	v_mul_f32_e32 v59, v59, v2
	v_mul_f32_e32 v80, v42, v42
	v_mul_f32_e32 v81, v43, v43
	v_add_f32_e32 v0, v74, v0
	v_fma_f32 v80, v58, v58, v80
	v_fma_f32 v81, v59, v59, v81
	v_add_f32_e32 v0, v75, v0
	v_add_f32_e32 v0, v80, v0
	v_add_f32_e32 v0, v81, v0
	v_add_f32_e32 v0, v18, v0
	v_add_f32_e32 v0, v19, v0
	v_add_f32_e32 v0, v20, v0
	v_add_f32_e32 v0, v21, v0
	v_add_f32_e32 v0, v22, v0
	v_add_f32_e32 v0, v23, v0
	ds_bpermute_b32 v2, v82, v0
	s_waitcnt lgkmcnt(0)
	v_add_f32_e32 v0, v0, v2
	v_fmamk_f32 v0, v0, 0x3c800000, v158
	v_cmp_gt_f32_e32 vcc, s33, v0
	v_mul_f32_e32 v2, 0x4b800000, v0
	s_nop 0
	v_cndmask_b32_e32 v0, v0, v2, vcc
	v_rsq_f32_e32 v0, v0
	s_nop 0
	v_mul_f32_e32 v2, 0x45800000, v0
	v_cndmask_b32_e32 v0, v0, v2, vcc
	v_mul_f32_e32 v18, v62, v0
	v_mul_f32_e32 v19, v63, v0
	v_mul_f32_e32 v20, v60, v0
	v_mul_f32_e32 v21, v61, v0
	v_mul_f32_e32 v14, v14, v0
	v_mul_f32_e32 v15, v15, v0
	v_mul_f32_e32 v12, v12, v0
	v_mul_f32_e32 v13, v13, v0
	v_mul_f32_e32 v4, v4, v0
	v_mul_f32_e32 v5, v5, v0
	v_mul_f32_e32 v6, v6, v0
	v_mul_f32_e32 v7, v7, v0
	s_waitcnt vmcnt(6)
	v_mul_f32_e32 v18, v24, v18
	v_mul_f32_e32 v19, v25, v19
	v_mul_f32_e32 v20, v26, v20
	v_mul_f32_e32 v21, v27, v21
	v_cvt_pk_bf16_f32 v18, v18, v19
	v_cvt_pk_bf16_f32 v19, v20, v21
	global_store_dwordx2 v[10:11], v[18:19], off offset:512
	v_mul_f32_e32 v18, v64, v0
	v_mul_f32_e32 v19, v65, v0
	v_mul_f32_e32 v20, v56, v0
	v_mul_f32_e32 v21, v57, v0
	s_waitcnt vmcnt(6)
	v_mul_f32_e32 v18, v28, v18
	v_mul_f32_e32 v19, v29, v19
	v_mul_f32_e32 v20, v30, v20
	v_mul_f32_e32 v21, v31, v21
	v_cvt_pk_bf16_f32 v18, v18, v19
	v_cvt_pk_bf16_f32 v19, v20, v21
	global_store_dwordx2 v[10:11], v[18:19], off offset:528
	v_mul_f32_e32 v18, v58, v0
	v_mul_f32_e32 v19, v59, v0
	s_waitcnt vmcnt(6)
	v_mul_f32_e32 v14, v46, v14
	v_mul_f32_e32 v15, v47, v15
	v_mul_f32_e32 v18, v44, v18
	v_mul_f32_e32 v19, v45, v19
	s_waitcnt vmcnt(5)
	v_mul_f32_e32 v12, v48, v12
	v_mul_f32_e32 v13, v49, v13
	v_cvt_pk_bf16_f32 v18, v18, v19
	v_cvt_pk_bf16_f32 v19, v14, v15
	v_mul_f32_e32 v14, v16, v0
	v_mul_f32_e32 v15, v17, v0
	v_cvt_pk_bf16_f32 v12, v12, v13
	v_mul_f32_e32 v14, v50, v14
	v_mul_f32_e32 v15, v51, v15
	global_store_dwordx2 v[10:11], v[18:19], off offset:544
	v_cvt_pk_bf16_f32 v13, v14, v15
	global_store_dwordx2 v[10:11], v[12:13], off offset:560
	v_mul_f32_e32 v12, v70, v0
	v_mul_f32_e32 v13, v71, v0
	v_mul_f32_e32 v14, v66, v0
	v_mul_f32_e32 v15, v67, v0
	s_waitcnt vmcnt(6)
	v_mul_f32_e32 v12, v52, v12
	v_mul_f32_e32 v13, v53, v13
	v_mul_f32_e32 v14, v54, v14
	v_mul_f32_e32 v15, v55, v15
	v_cvt_pk_bf16_f32 v12, v12, v13
	v_cvt_pk_bf16_f32 v13, v14, v15
	global_store_dwordx2 v[10:11], v[12:13], off offset:576
	v_mul_f32_e32 v12, v76, v0
	v_mul_f32_e32 v13, v77, v0
	v_mul_f32_e32 v14, v40, v0
	v_mul_f32_e32 v15, v41, v0
	s_waitcnt vmcnt(6)
	v_mul_f32_e32 v12, v32, v12
	v_mul_f32_e32 v13, v33, v13
	v_mul_f32_e32 v14, v34, v14
	v_mul_f32_e32 v15, v35, v15
	v_cvt_pk_bf16_f32 v12, v12, v13
	v_cvt_pk_bf16_f32 v13, v14, v15
	global_store_dwordx2 v[10:11], v[12:13], off offset:592
	v_mul_f32_e32 v12, v42, v0
	v_mul_f32_e32 v13, v43, v0
	s_waitcnt vmcnt(6)
	v_mul_f32_e32 v4, v38, v4
	v_mul_f32_e32 v5, v39, v5
	v_mul_f32_e32 v12, v36, v12
	v_mul_f32_e32 v13, v37, v13
	s_nop 0
	v_cvt_pk_bf16_f32 v12, v12, v13
	v_cvt_pk_bf16_f32 v13, v4, v5
	global_load_dwordx4 v[2:5], v3, s[30:31] offset:1248
	s_waitcnt vmcnt(0)
	v_mul_f32_e32 v2, v2, v6
	v_mul_f32_e32 v3, v3, v7
	v_mul_f32_e32 v6, v8, v0
	v_mul_f32_e32 v7, v9, v0
	v_cvt_pk_bf16_f32 v2, v2, v3
	v_mul_f32_e32 v4, v4, v6
	v_mul_f32_e32 v5, v5, v7
	global_store_dwordx2 v[10:11], v[12:13], off offset:608
	v_cvt_pk_bf16_f32 v3, v4, v5
	global_store_dwordx2 v[10:11], v[2:3], off offset:624

; DI float softplusf_(float z) { return fmaxf(z, 0.f) + __logf(1.f + __expf(-fabsf(z))); }
; DI void stick_item(const u16* R, const u16* T, const float* gh, u16* obuf, int hh, int qtile, float kmax2) {
;     ...
;     const int nb = n0 + 8 * h2;
;     float ra = 0.f, rb = 0.f;
; #pragma unroll
;     for (int i = 0; i < 16; ++i) {
;       const int n = nb + (i & 7) + 16 * (i >> 3);
;       sp[i] = (n < tq) ? softplusf_(s[i]) : 0.f;
;       if (i < 8) ra += sp[i]; else rb += sp[i];
;     }
;     const float pa = __shfl_xor(ra, 32), pb = __shfl_xor(rb, 32);
;     const float offB = carry + (h2 ? 0.f : pb);
;     const float offA = carry + rb + pb + (h2 ? 0.f : pa);
;     float a[16];
;     float run = offB;
; #pragma unroll
;     for (int i = 15; i >= 8; --i) {
;       const int n = nb + (i & 7) + 16;
;       run += sp[i];
;       a[i] = (n < tq) ? __expf(s[i] - run) : 0.f;
;     }
;     run = offA;
; #pragma unroll
;     for (int i = 7; i >= 0; --i) {
;       const int n = nb + (i & 7);
;       run += sp[i];
;       a[i] = (n < tq) ? __expf(s[i] - run) : 0.f;
;     }
;     carry += (ra + rb) + (pa + pb);
;     pv_tile(cur, a, st);
;     if (__all((zmax - carry) < -110.f)) break;
;     cur = nxt;
;   }
.LBB0_747:
	s_or_b64 exec, exec, s[90:91]
	v_add_f32_e32 v138, 0, v122
	v_add_f32_e32 v138, v138, v123
	v_add_f32_e32 v138, v138, v124
	v_add_f32_e32 v138, v138, v125
	v_add_f32_e32 v138, v138, v135
	v_add_f32_e32 v139, 0, v0
	v_add_f32_e32 v138, v138, v136
	v_add_f32_e32 v139, v139, v114
	v_add_f32_e32 v138, v138, v137
	v_add_f32_e32 v139, v139, v118
	v_add_f32_e32 v139, v139, v115
	v_add_f32_e32 v138, v138, v119
	v_add_f32_e32 v140, v139, v116
	ds_bpermute_b32 v139, v127, v138
	v_add_f32_e32 v140, v140, v117
	v_add_f32_e32 v140, v140, v120
	v_add_f32_e32 v140, v140, v121
	ds_bpermute_b32 v141, v127, v140
	s_waitcnt lgkmcnt(1)
	v_cndmask_b32_e64 v142, 0, v139, s[46:47]
	v_add_f32_e32 v142, v132, v142
	v_add_f32_e32 v119, v119, v142
	v_sub_f32_e32 v49, v49, v119
	v_add_f32_e32 v119, v137, v119
	v_sub_f32_e32 v48, v48, v119
	v_add_f32_e32 v119, v136, v119
	v_sub_f32_e32 v47, v47, v119
	v_add_f32_e32 v119, v135, v119
	v_sub_f32_e32 v46, v46, v119
	v_add_f32_e32 v119, v125, v119
	v_sub_f32_e32 v45, v45, v119
	v_add_f32_e32 v119, v124, v119
	v_sub_f32_e32 v44, v44, v119
	v_add_f32_e32 v119, v123, v119
	v_add_f32_e32 v142, v132, v138
	v_sub_f32_e32 v43, v43, v119
	v_add_f32_e32 v119, v122, v119
	s_waitcnt lgkmcnt(0)
	v_cndmask_b32_e64 v143, 0, v141, s[46:47]
	v_sub_f32_e32 v42, v42, v119
	v_add_f32_e32 v119, v142, v139
	v_add_f32_e32 v119, v143, v119
	v_add_f32_e32 v119, v121, v119
	v_sub_f32_e32 v41, v41, v119
	v_add_f32_e32 v119, v120, v119
	v_add_f32_e32 v117, v117, v119
	v_add_f32_e32 v116, v116, v117
	v_add_f32_e32 v115, v115, v116
	v_sub_f32_e32 v37, v37, v115
	v_add_f32_e32 v115, v118, v115
	v_add_f32_e32 v114, v114, v115
	v_add_f32_e32 v0, v0, v114
	v_sub_f32_e32 v40, v40, v119
	v_sub_f32_e32 v39, v39, v117
	v_sub_f32_e32 v38, v38, v116
	v_sub_f32_e32 v36, v36, v115
	v_sub_f32_e32 v35, v35, v114
	v_sub_f32_e32 v0, v34, v0
	v_mul_f32_e32 v41, 0x3fb8aa3b, v41
	v_mul_f32_e32 v40, 0x3fb8aa3b, v40
	v_mul_f32_e32 v39, 0x3fb8aa3b, v39
	v_mul_f32_e32 v38, 0x3fb8aa3b, v38
	v_mul_f32_e32 v37, 0x3fb8aa3b, v37
	v_mul_f32_e32 v36, 0x3fb8aa3b, v36
	v_mul_f32_e32 v35, 0x3fb8aa3b, v35
	v_mul_f32_e32 v0, 0x3fb8aa3b, v0
	v_exp_f32_e32 v41, v41
	v_exp_f32_e32 v40, v40
	v_exp_f32_e32 v39, v39
	v_exp_f32_e32 v38, v38
	v_exp_f32_e32 v37, v37
	v_exp_f32_e32 v36, v36
	v_exp_f32_e32 v35, v35
	v_exp_f32_e32 v0, v0
	v_cndmask_b32_e64 v41, 0, v41, s[62:63]
	v_cndmask_b32_e64 v40, 0, v40, s[58:59]
	v_cndmask_b32_e64 v39, 0, v39, s[56:57]
	v_cndmask_b32_e64 v38, 0, v38, s[54:55]
	v_cndmask_b32_e64 v37, 0, v37, s[52:53]
	v_cndmask_b32_e64 v36, 0, v36, s[50:51]
	v_cndmask_b32_e64 v34, 0, v35, s[48:49]
	v_cndmask_b32_e32 v0, 0, v0, vcc
	v_cvt_pk_bf16_f32 v34, v0, v34
	v_cvt_pk_bf16_f32 v35, v36, v37
	v_cvt_pk_bf16_f32 v36, v38, v39
	v_cvt_pk_bf16_f32 v37, v40, v41
	v_mul_f32_e32 v49, 0x3fb8aa3b, v49
	v_mul_f32_e32 v48, 0x3fb8aa3b, v48
	v_mfma_f32_32x32x16_bf16 v[18:33], v[70:73], v[34:37], v[18:33]
	v_mul_f32_e32 v47, 0x3fb8aa3b, v47
	v_mul_f32_e32 v46, 0x3fb8aa3b, v46
	v_mul_f32_e32 v45, 0x3fb8aa3b, v45
	v_mul_f32_e32 v44, 0x3fb8aa3b, v44
	v_mul_f32_e32 v43, 0x3fb8aa3b, v43
	v_mul_f32_e32 v42, 0x3fb8aa3b, v42
	v_exp_f32_e32 v49, v49
	v_mfma_f32_32x32x16_bf16 v[2:17], v[74:77], v[34:37], v[2:17]
	v_exp_f32_e32 v48, v48
	v_exp_f32_e32 v47, v47
	v_exp_f32_e32 v46, v46
	v_exp_f32_e32 v45, v45
	v_exp_f32_e32 v44, v44
	v_exp_f32_e32 v43, v43
	v_exp_f32_e32 v42, v42
	v_cndmask_b32_e64 v49, 0, v49, s[76:77]
	v_cndmask_b32_e64 v48, 0, v48, s[74:75]
	v_cndmask_b32_e64 v47, 0, v47, s[72:73]
	v_cndmask_b32_e64 v46, 0, v46, s[70:71]
	v_cndmask_b32_e64 v45, 0, v45, s[68:69]
	v_cndmask_b32_e64 v0, 0, v44, s[66:67]
	v_cndmask_b32_e64 v38, 0, v43, s[64:65]
	v_cndmask_b32_e64 v39, 0, v42, s[60:61]
	v_add_f32_e32 v34, v140, v138
	v_add_f32_e32 v35, v141, v139
	v_cvt_pk_bf16_f32 v38, v39, v38
	v_cvt_pk_bf16_f32 v39, v0, v45
	v_cvt_pk_bf16_f32 v40, v46, v47
	v_cvt_pk_bf16_f32 v41, v48, v49
	v_add_f32_e32 v0, v34, v35
	v_add_f32_e32 v132, v132, v0
	v_mfma_f32_32x32x16_bf16 v[18:33], v[66:69], v[38:41], v[18:33]
	v_sub_f32_e32 v0, v133, v132
	s_mov_b32 s10, 0xc2dc0000
	v_cmp_gt_f32_e32 vcc, s10, v0
	s_cmp_lg_u64 vcc, exec
	s_cselect_b64 s[10:11], -1, 0
	s_cmpk_lg_i32 s2, 0xffe0
	s_cselect_b64 s[12:13], -1, 0
	v_mfma_f32_32x32x16_bf16 v[2:17], v[78:81], v[38:41], v[2:17]
	s_and_b64 s[10:11], s[12:13], s[10:11]
	s_waitcnt vmcnt(7)
	v_mov_b64_e32 v[34:35], v[94:95]
	s_waitcnt vmcnt(6)
	v_mov_b64_e32 v[120:121], v[92:93]
	s_waitcnt vmcnt(5)
	v_mov_b64_e32 v[124:125], v[88:89]
	s_waitcnt vmcnt(4)
	v_mov_b64_e32 v[116:117], v[84:85]
	s_waitcnt vmcnt(3)
	v_mov_b64_e32 v[70:71], v[98:99]
	s_waitcnt vmcnt(2)
	v_mov_b64_e32 v[66:67], v[102:103]
	s_waitcnt vmcnt(1)
	v_mov_b64_e32 v[74:75], v[110:111]
	s_waitcnt vmcnt(0)
	v_mov_b64_e32 v[78:79], v[106:107]
	s_sub_i32 s2, s2, 32
	s_and_b64 vcc, exec, s[10:11]
	v_mov_b64_e32 v[36:37], v[96:97]
	v_mov_b64_e32 v[118:119], v[90:91]
	v_mov_b64_e32 v[122:123], v[86:87]
	v_mov_b64_e32 v[114:115], v[82:83]
	v_mov_b64_e32 v[72:73], v[100:101]
	v_mov_b64_e32 v[68:69], v[104:105]
	v_mov_b64_e32 v[76:77], v[112:113]
	v_mov_b64_e32 v[80:81], v[108:109]
	s_cbranch_vccz .LBB0_782

; DI void write_headnorm(const f32x16& o0, const f32x16& o1, const float* __restrict__ gh, u16* obuf, int tq, int colbase) {
;   const int h2 = (TIDX & 63) >> 5;
;   float ss = 0.f;
; #pragma unroll
;   for (int i = 0; i < 16; ++i) ss += o0[i] * o0[i] + o1[i] * o1[i];
;   ss += __shfl_xor(ss, 32);
;   const float rstd = rsqrtf(ss * (1.f / 64.f) + 1e-6f);
; #pragma unroll
;   for (int dt = 0; dt < 2; ++dt)
; #pragma unroll
;     for (int g = 0; g < 4; ++g) {
;       const int d = dt * 32 + 8 * g + 4 * h2;
;       f32x4 gg = *reinterpret_cast<const f32x4*>(gh + d);
;       float v0 = (dt ? o1[4 * g + 0] : o0[4 * g + 0]) * rstd * gg[0];
;       float v1 = (dt ? o1[4 * g + 1] : o0[4 * g + 1]) * rstd * gg[1];
;       float v2 = (dt ? o1[4 * g + 2] : o0[4 * g + 2]) * rstd * gg[2];
;       float v3 = (dt ? o1[4 * g + 3] : o0[4 * g + 3]) * rstd * gg[3];
;       u32x2 pk = {pack2(v0, v1), pack2(v2, v3)};
;       *reinterpret_cast<u32x2*>(obuf + (size_t)tq * DM + colbase + d) = pk;
;     }
; }
.LBB0_782:
	v_mul_f32_e32 v34, v2, v2
	v_mul_f32_e32 v35, v3, v3
	v_fmac_f32_e32 v34, v18, v18
	v_fmac_f32_e32 v35, v19, v19
	v_add_f32_e32 v34, v34, v35
	v_mul_f32_e32 v35, v4, v4
	v_fmac_f32_e32 v35, v20, v20
	v_add_f32_e32 v34, v35, v34
	v_mul_f32_e32 v35, v5, v5
	v_fmac_f32_e32 v35, v21, v21
	v_add_f32_e32 v34, v35, v34
	v_mul_f32_e32 v35, v6, v6
	v_fmac_f32_e32 v35, v22, v22
	v_add_f32_e32 v34, v35, v34
	v_mul_f32_e32 v35, v7, v7
	v_fmac_f32_e32 v35, v23, v23
	v_add_f32_e32 v44, v35, v34
	v_mul_f32_e32 v34, v8, v8
	v_mul_f32_e32 v35, v9, v9
	v_mul_f32_e32 v36, v10, v10
	v_mul_f32_e32 v37, v11, v11
	v_fma_f32 v34, v24, v24, v34
	v_fma_f32 v35, v25, v25, v35
	v_fma_f32 v36, v26, v26, v36
	v_fma_f32 v37, v27, v27, v37
	v_add_f32_e32 v34, v34, v44
	v_add_f32_e32 v34, v35, v34
	v_mul_f32_e32 v38, v12, v12
	v_mul_f32_e32 v39, v13, v13
	v_add_f32_e32 v34, v36, v34
	v_fma_f32 v38, v28, v28, v38
	v_fma_f32 v39, v29, v29, v39
	v_add_f32_e32 v34, v37, v34
	v_mul_f32_e32 v40, v14, v14
	v_mul_f32_e32 v41, v15, v15
	v_add_f32_e32 v34, v38, v34
	v_fma_f32 v40, v30, v30, v40
	v_fma_f32 v41, v31, v31, v41
	v_add_f32_e32 v34, v39, v34
	v_mul_f32_e32 v42, v16, v16
	v_mul_f32_e32 v43, v17, v17
	v_add_f32_e32 v34, v40, v34
	v_fma_f32 v42, v32, v32, v42
	v_fma_f32 v43, v33, v33, v43
	v_add_f32_e32 v34, v41, v34
	v_add_f32_e32 v34, v42, v34
	v_add_f32_e32 v34, v43, v34
	ds_bpermute_b32 v35, v127, v34
	v_mov_b32_e32 v0, v159
	s_lshl_b32 s2, s94, 2
	v_lshrrev_b32_e32 v0, 3, v0
	s_waitcnt lgkmcnt(0)
	v_add_f32_e32 v34, v34, v35
	v_fmamk_f32 v34, v34, 0x3c800000, v158
	v_cmp_gt_f32_e32 vcc, s33, v34
	v_mul_f32_e32 v35, 0x4b800000, v34
	v_readlane_b32 s10, v255, 39
	v_cndmask_b32_e32 v34, v34, v35, vcc
	v_rsq_f32_e32 v34, v34
	s_add_u32 s30, s21, s2
	v_readlane_b32 s11, v255, 40
	s_addc_u32 s31, s22, 0
	v_mul_f32_e32 v35, 0x45800000, v34
	v_cndmask_b32_e32 v34, v34, v35, vcc
	v_and_b32_e32 v35, 4, v0
	v_lshlrev_b32_e32 v0, 11, v126
	v_lshl_add_u64 v[36:37], s[10:11], 0, v[0:1]
	s_lshl_b32 s2, s94, 1
	v_lshlrev_b32_e32 v42, 2, v35
	v_lshl_add_u64 v[40:41], v[36:37], 0, s[2:3]
	global_load_dwordx4 v[36:39], v42, s[30:31] offset:3072
	v_mul_f32_e32 v18, v18, v34
	v_mul_f32_e32 v19, v19, v34
	v_mul_f32_e32 v20, v20, v34
	v_mul_f32_e32 v21, v21, v34
	v_lshlrev_b32_e32 v0, 1, v35
	v_mul_f32_e32 v2, v2, v34
	v_mul_f32_e32 v3, v3, v34
	v_mul_f32_e32 v4, v4, v34
	v_mul_f32_e32 v5, v5, v34
	v_mul_f32_e32 v6, v6, v34
	v_mul_f32_e32 v7, v7, v34
	s_waitcnt vmcnt(0)
	v_mul_f32_e32 v18, v36, v18
	v_mul_f32_e32 v19, v37, v19
	v_mul_f32_e32 v20, v38, v20
	v_mul_f32_e32 v21, v39, v21
	v_cvt_pk_bf16_f32 v36, v18, v19
	v_cvt_pk_bf16_f32 v37, v20, v21
	v_lshl_add_u64 v[18:19], v[40:41], 0, v[0:1]
	global_store_dwordx2 v[18:19], v[36:37], off offset:1536
	global_load_dwordx4 v[36:39], v42, s[30:31] offset:3104
	v_mul_f32_e32 v20, v22, v34
	v_mul_f32_e32 v21, v23, v34
	v_mul_f32_e32 v22, v24, v34
	v_mul_f32_e32 v23, v25, v34
	v_mul_f32_e32 v24, v26, v34
	v_mul_f32_e32 v25, v27, v34
	s_waitcnt vmcnt(0)
	v_mul_f32_e32 v20, v36, v20
	v_mul_f32_e32 v21, v37, v21
	v_mul_f32_e32 v22, v38, v22
	v_mul_f32_e32 v23, v39, v23
	v_cvt_pk_bf16_f32 v20, v20, v21
	v_cvt_pk_bf16_f32 v21, v22, v23
	global_store_dwordx2 v[18:19], v[20:21], off offset:1552
	global_load_dwordx4 v[20:23], v42, s[30:31] offset:3136
	s_waitcnt vmcnt(0)
	v_mul_f32_e32 v20, v20, v24
	v_mul_f32_e32 v21, v21, v25
	v_mul_f32_e32 v24, v28, v34
	v_mul_f32_e32 v25, v29, v34
	v_cvt_pk_bf16_f32 v20, v20, v21
	v_mul_f32_e32 v22, v22, v24
	v_mul_f32_e32 v23, v23, v25
	v_mul_f32_e32 v24, v30, v34
	v_mul_f32_e32 v25, v31, v34
	v_cvt_pk_bf16_f32 v21, v22, v23
	global_store_dwordx2 v[18:19], v[20:21], off offset:1568
	global_load_dwordx4 v[20:23], v42, s[30:31] offset:3168
	s_waitcnt vmcnt(0)
	v_mul_f32_e32 v20, v20, v24
	v_mul_f32_e32 v21, v21, v25
	v_mul_f32_e32 v24, v32, v34
	v_mul_f32_e32 v25, v33, v34
	v_cvt_pk_bf16_f32 v20, v20, v21
	v_mul_f32_e32 v22, v22, v24
	v_mul_f32_e32 v23, v23, v25
	s_nop 0
	v_cvt_pk_bf16_f32 v21, v22, v23
	global_store_dwordx2 v[18:19], v[20:21], off offset:1584
	global_load_dwordx4 v[20:23], v42, s[30:31] offset:3200
	s_waitcnt vmcnt(0)
	v_mul_f32_e32 v2, v20, v2
	v_mul_f32_e32 v3, v21, v3
	v_mul_f32_e32 v4, v22, v4
	v_mul_f32_e32 v5, v23, v5
	v_cvt_pk_bf16_f32 v2, v2, v3
	v_cvt_pk_bf16_f32 v3, v4, v5
	global_store_dwordx2 v[18:19], v[2:3], off offset:1600
	global_load_dwordx4 v[2:5], v42, s[30:31] offset:3232
	s_waitcnt vmcnt(0)
	v_mul_f32_e32 v2, v6, v2
	v_mul_f32_e32 v3, v7, v3
	v_mul_f32_e32 v6, v8, v34
	v_mul_f32_e32 v7, v9, v34
	v_cvt_pk_bf16_f32 v2, v2, v3
	v_mul_f32_e32 v4, v6, v4
	v_mul_f32_e32 v5, v7, v5
	v_mul_f32_e32 v6, v10, v34
	v_mul_f32_e32 v7, v11, v34
	v_cvt_pk_bf16_f32 v3, v4, v5
	global_store_dwordx2 v[18:19], v[2:3], off offset:1616
	global_load_dwordx4 v[2:5], v42, s[30:31] offset:3264
	s_waitcnt vmcnt(0)
	v_mul_f32_e32 v2, v6, v2
	v_mul_f32_e32 v3, v7, v3
	v_mul_f32_e32 v6, v12, v34
	v_mul_f32_e32 v7, v13, v34
	v_cvt_pk_bf16_f32 v2, v2, v3
	v_mul_f32_e32 v4, v6, v4
	v_mul_f32_e32 v5, v7, v5
	v_mul_f32_e32 v6, v14, v34
	v_mul_f32_e32 v7, v15, v34
	v_cvt_pk_bf16_f32 v3, v4, v5
	global_store_dwordx2 v[18:19], v[2:3], off offset:1632
	global_load_dwordx4 v[2:5], v42, s[30:31] offset:3296
	s_mov_b64 s[30:31], 0
	s_waitcnt vmcnt(0)
	v_mul_f32_e32 v2, v6, v2
	v_mul_f32_e32 v3, v7, v3
	v_mul_f32_e32 v6, v16, v34
	v_mul_f32_e32 v7, v17, v34
	v_cvt_pk_bf16_f32 v2, v2, v3
	v_mul_f32_e32 v4, v6, v4
	v_mul_f32_e32 v5, v7, v5
	s_nop 0
	v_cvt_pk_bf16_f32 v3, v4, v5
	global_store_dwordx2 v[18:19], v[2:3], off offset:1648

; #define NEG_INF (-__builtin_inff())
; DI void softmax_step(float (&sc)[16], AState& st, const KV& kv) {
;   float mx = NEG_INF;
; #pragma unroll
;   for (int i = 0; i < 16; ++i) mx = fmaxf(mx, sc[i]);
;   mx = fmaxf(mx, __shfl_xor(mx, 32));
;   const float mnew = fmaxf(st.m, mx);
;   const float meff = (mnew == NEG_INF) ? 0.f : mnew;
;   const float alpha = __expf(st.m - meff);
;   float rs = 0.f;
; #pragma unroll
;   for (int i = 0; i < 16; ++i) { sc[i] = __expf(sc[i] - meff); rs += sc[i]; }
;   st.l = st.l * alpha + rs;
;   st.m = mnew;
;   if (__any(alpha != 1.f)) {
; #pragma unroll
;     for (int i = 0; i < 16; ++i) { st.o0[i] *= alpha; st.o1[i] *= alpha; }
; DI void band_tile(const KV& kv, const bf16x8 (&q)[4], AState& st, const Fam& f, int n0, int tq, int wtok, float nslope) {
;   const int h2 = (TIDX & 63) >> 5;
;   f32x16 s = qk_tile(kv, q);
;   float sc[16];
;   const int nb = n0 + 8 * h2;
; #pragma unroll
;   for (int i = 0; i < 16; ++i) {
;     const int n = nb + (i & 7) + 16 * (i >> 3);
;     const int stok = n * f.kstride + f.koff;
;     const int dist = tq - stok;
;     const bool valid = (stok >= 0) && (dist >= 0) && (dist <= wtok);
;     sc[i] = valid ? s[i] + nslope * (float)dist : NEG_INF;
;   }
;   softmax_step(sc, st, kv);
; }
.LBB0_788:
	v_mfma_f32_32x32x16_bf16 v[34:49], v[34:37], v[82:85], 0
	v_mov_b32_e32 v0, v159
	s_sub_i32 s14, s49, 32
	v_lshlrev_b32_e32 v0, 2, v0
	s_cmp_gt_i32 s14, -1
	s_cselect_b64 s[46:47], -1, 0
	v_mfma_f32_32x32x16_bf16 v[34:49], v[114:117], v[86:89], v[34:49]
	v_add_u32_e32 v114, s11, v133
	v_and_b32_e32 v115, 0x80, v0
	v_sub_u32_e32 v0, v114, v115
	v_mfma_f32_32x32x16_bf16 v[34:49], v[118:121], v[90:93], v[34:49]
	v_mfma_f32_32x32x16_bf16 v[34:49], v[122:125], v[94:97], v[34:49]
	s_nop 11
	v_mov_b32_e32 v196, v0
	v_add_u32_e32 v197, -16, v0
	v_cmp_gt_u32_e32 vcc, s8, v196
	v_cmp_gt_u32_e64 s[46:47], s8, v197
	v_cvt_f32_i32_e32 v196, v196
	v_cvt_f32_i32_e32 v197, v197
	v_fma_f32 v34, -v189, v196, v34
	v_fma_f32 v35, -v189, v197, v35
	v_cndmask_b32_e32 v34, v184, v34, vcc
	v_cndmask_b32_e64 v35, v184, v35, s[46:47]
	v_add_u32_e32 v196, 0xffffffe0, v0
	v_add_u32_e32 v197, 0xffffffd0, v0
	v_cmp_gt_u32_e32 vcc, s8, v196
	v_cmp_gt_u32_e64 s[46:47], s8, v197
	v_cvt_f32_i32_e32 v196, v196
	v_cvt_f32_i32_e32 v197, v197
	v_fma_f32 v36, -v189, v196, v36
	v_fma_f32 v37, -v189, v197, v37
	v_cndmask_b32_e32 v36, v184, v36, vcc
	v_cndmask_b32_e64 v37, v184, v37, s[46:47]
	v_add_u32_e32 v196, 0xffffffc0, v0
	v_add_u32_e32 v197, 0xffffffb0, v0
	v_cmp_gt_u32_e32 vcc, s8, v196
	v_cmp_gt_u32_e64 s[46:47], s8, v197
	v_cvt_f32_i32_e32 v196, v196
	v_cvt_f32_i32_e32 v197, v197
	v_fma_f32 v38, -v189, v196, v38
	v_fma_f32 v39, -v189, v197, v39
	v_cndmask_b32_e32 v38, v184, v38, vcc
	v_cndmask_b32_e64 v39, v184, v39, s[46:47]
	v_add_u32_e32 v196, 0xffffffa0, v0
	v_add_u32_e32 v197, 0xffffff90, v0
	v_cmp_gt_u32_e32 vcc, s8, v196
	v_cmp_gt_u32_e64 s[46:47], s8, v197
	v_cvt_f32_i32_e32 v196, v196
	v_cvt_f32_i32_e32 v197, v197
	v_fma_f32 v40, -v189, v196, v40
	v_fma_f32 v41, -v189, v197, v41
	v_cndmask_b32_e32 v40, v184, v40, vcc
	v_cndmask_b32_e64 v41, v184, v41, s[46:47]
	v_add_u32_e32 v196, 0xffffff00, v0
	v_add_u32_e32 v197, 0xfffffef0, v0
	v_cmp_gt_u32_e32 vcc, s8, v196
	v_cmp_gt_u32_e64 s[46:47], s8, v197
	v_cvt_f32_i32_e32 v196, v196
	v_cvt_f32_i32_e32 v197, v197
	v_fma_f32 v42, -v189, v196, v42
	v_fma_f32 v43, -v189, v197, v43
	v_cndmask_b32_e32 v42, v184, v42, vcc
	v_cndmask_b32_e64 v43, v184, v43, s[46:47]
	v_add_u32_e32 v196, 0xfffffee0, v0
	v_add_u32_e32 v197, 0xfffffed0, v0
	v_cmp_gt_u32_e32 vcc, s8, v196
	v_cmp_gt_u32_e64 s[46:47], s8, v197
	v_cvt_f32_i32_e32 v196, v196
	v_cvt_f32_i32_e32 v197, v197
	v_fma_f32 v44, -v189, v196, v44
	v_fma_f32 v45, -v189, v197, v45
	v_cndmask_b32_e32 v44, v184, v44, vcc
	v_cndmask_b32_e64 v45, v184, v45, s[46:47]
	v_add_u32_e32 v196, 0xfffffec0, v0
	v_add_u32_e32 v197, 0xfffffeb0, v0
	v_cmp_gt_u32_e32 vcc, s8, v196
	v_cmp_gt_u32_e64 s[46:47], s8, v197
	v_cvt_f32_i32_e32 v196, v196
	v_cvt_f32_i32_e32 v197, v197
	v_fma_f32 v46, -v189, v196, v46
	v_fma_f32 v47, -v189, v197, v47
	v_cndmask_b32_e32 v46, v184, v46, vcc
	v_cndmask_b32_e64 v47, v184, v47, s[46:47]
	v_add_u32_e32 v196, 0xfffffea0, v0
	v_add_u32_e32 v197, 0xfffffe90, v0
	v_cmp_gt_u32_e32 vcc, s8, v196
	v_cmp_gt_u32_e64 s[46:47], s8, v197
	v_cvt_f32_i32_e32 v196, v196
	v_cvt_f32_i32_e32 v197, v197
	v_fma_f32 v48, -v189, v196, v48
	v_fma_f32 v49, -v189, v197, v49
	v_cndmask_b32_e32 v48, v184, v48, vcc
	v_cndmask_b32_e64 v49, v184, v49, s[46:47]
	v_max3_f32 v0, v34, s35, v35
	v_max3_f32 v0, v0, v36, v37
	v_max3_f32 v0, v0, v38, v39
	v_mbcnt_hi_u32_b32 v114, -1, v180
	v_max3_f32 v0, v0, v40, v41
	v_and_b32_e32 v116, 64, v114
	v_max3_f32 v0, v0, v42, v43
	v_xor_b32_e32 v115, 32, v114
	v_add_u32_e32 v116, 64, v116
	v_max3_f32 v0, v0, v44, v45
	v_cmp_lt_i32_e32 vcc, v115, v116
	v_max3_f32 v0, v0, v46, v47
	v_max3_f32 v0, v0, v48, v49
	v_cndmask_b32_e32 v114, v114, v115, vcc
	v_lshlrev_b32_e32 v114, 2, v114
	ds_bpermute_b32 v114, v114, v0
	s_waitcnt lgkmcnt(0)
	v_max3_f32 v131, v135, v0, v114
	v_cmp_neq_f32_e32 vcc, s35, v131
	s_nop 1
	v_cndmask_b32_e32 v114, 0, v131, vcc
	v_sub_f32_e32 v0, v135, v114
	v_mul_f32_e32 v0, 0x3fb8aa3b, v0
	v_exp_f32_e32 v0, v0
	s_nop 0
	v_cmp_neq_f32_e32 vcc, 1.0, v0
	s_cbranch_vccz .LBB0_790
	v_mul_f32_e32 v32, v32, v0
	v_mul_f32_e32 v33, v33, v0
	v_mul_f32_e32 v30, v30, v0
	v_mul_f32_e32 v31, v31, v0
	v_mul_f32_e32 v28, v28, v0
	v_mul_f32_e32 v29, v29, v0
	v_mul_f32_e32 v26, v26, v0
	v_mul_f32_e32 v27, v27, v0
	v_mul_f32_e32 v24, v24, v0
	v_mul_f32_e32 v25, v25, v0
	v_mul_f32_e32 v22, v22, v0
	v_mul_f32_e32 v23, v23, v0
	v_mul_f32_e32 v20, v20, v0
	v_mul_f32_e32 v21, v21, v0
	v_mul_f32_e32 v18, v18, v0
	v_mul_f32_e32 v19, v19, v0
	v_mul_f32_e32 v16, v16, v0
	v_mul_f32_e32 v17, v17, v0
	v_mul_f32_e32 v14, v14, v0
	v_mul_f32_e32 v15, v15, v0
	v_mul_f32_e32 v12, v12, v0
	v_mul_f32_e32 v13, v13, v0
	v_mul_f32_e32 v10, v10, v0
	v_mul_f32_e32 v11, v11, v0
	v_mul_f32_e32 v8, v8, v0
	v_mul_f32_e32 v9, v9, v0
	v_mul_f32_e32 v6, v6, v0
	v_mul_f32_e32 v7, v7, v0
	v_mul_f32_e32 v4, v4, v0
	v_mul_f32_e32 v5, v5, v0
	v_mul_f32_e32 v2, v2, v0
	v_mul_f32_e32 v3, v3, v0

; #define NEG_INF (-__builtin_inff())
; DI void softmax_step(float (&sc)[16], AState& st, const KV& kv) {
;   float mx = NEG_INF;
; #pragma unroll
;   for (int i = 0; i < 16; ++i) mx = fmaxf(mx, sc[i]);
;   mx = fmaxf(mx, __shfl_xor(mx, 32));
;   const float mnew = fmaxf(st.m, mx);
;   const float meff = (mnew == NEG_INF) ? 0.f : mnew;
;   const float alpha = __expf(st.m - meff);
;   float rs = 0.f;
; #pragma unroll
;   for (int i = 0; i < 16; ++i) { sc[i] = __expf(sc[i] - meff); rs += sc[i]; }
;   st.l = st.l * alpha + rs;
;   st.m = mnew;
;   if (__any(alpha != 1.f)) {
; #pragma unroll
;     for (int i = 0; i < 16; ++i) { st.o0[i] *= alpha; st.o1[i] *= alpha; }
; DI void band_tile(const KV& kv, const bf16x8 (&q)[4], AState& st, const Fam& f, int n0, int tq, int wtok, float nslope) {
;   const int h2 = (TIDX & 63) >> 5;
;   f32x16 s = qk_tile(kv, q);
;   float sc[16];
;   const int nb = n0 + 8 * h2;
; #pragma unroll
;   for (int i = 0; i < 16; ++i) {
;     const int n = nb + (i & 7) + 16 * (i >> 3);
;     const int stok = n * f.kstride + f.koff;
;     const int dist = tq - stok;
;     const bool valid = (stok >= 0) && (dist >= 0) && (dist <= wtok);
;     sc[i] = valid ? s[i] + nslope * (float)dist : NEG_INF;
;   }
;   softmax_step(sc, st, kv);
; }
.LBB0_796:
	v_mfma_f32_32x32x16_bf16 v[34:49], v[34:37], v[82:85], 0
	v_mov_b32_e32 v0, v159
	s_sub_i32 s14, s10, 32
	s_cmp_gt_i32 s14, -1
	s_cselect_b64 s[46:47], -1, 0
	v_mfma_f32_32x32x16_bf16 v[34:49], v[114:117], v[86:89], v[34:49]
	v_and_b32_e32 v114, 32, v0
	v_add_u32_e32 v0, s23, v133
	v_sub_u32_e32 v0, v0, v114
	v_mfma_f32_32x32x16_bf16 v[34:49], v[118:121], v[90:93], v[34:49]
	v_mfma_f32_32x32x16_bf16 v[34:49], v[122:125], v[94:97], v[34:49]
	s_nop 11
	v_mov_b32_e32 v196, v0
	v_add_u32_e32 v197, -4, v0
	v_cmp_gt_u32_e32 vcc, s34, v196
	v_cmp_gt_u32_e64 s[46:47], s34, v197
	v_cvt_f32_i32_e32 v196, v196
	v_cvt_f32_i32_e32 v197, v197
	v_fma_f32 v34, -v189, v196, v34
	v_fma_f32 v35, -v189, v197, v35
	v_cndmask_b32_e32 v34, v184, v34, vcc
	v_cndmask_b32_e64 v35, v184, v35, s[46:47]
	v_add_u32_e32 v196, -8, v0
	v_add_u32_e32 v197, -12, v0
	v_cmp_gt_u32_e32 vcc, s34, v196
	v_cmp_gt_u32_e64 s[46:47], s34, v197
	v_cvt_f32_i32_e32 v196, v196
	v_cvt_f32_i32_e32 v197, v197
	v_fma_f32 v36, -v189, v196, v36
	v_fma_f32 v37, -v189, v197, v37
	v_cndmask_b32_e32 v36, v184, v36, vcc
	v_cndmask_b32_e64 v37, v184, v37, s[46:47]
	v_add_u32_e32 v196, -16, v0
	v_add_u32_e32 v197, 0xffffffec, v0
	v_cmp_gt_u32_e32 vcc, s34, v196
	v_cmp_gt_u32_e64 s[46:47], s34, v197
	v_cvt_f32_i32_e32 v196, v196
	v_cvt_f32_i32_e32 v197, v197
	v_fma_f32 v38, -v189, v196, v38
	v_fma_f32 v39, -v189, v197, v39
	v_cndmask_b32_e32 v38, v184, v38, vcc
	v_cndmask_b32_e64 v39, v184, v39, s[46:47]
	v_add_u32_e32 v196, 0xffffffe8, v0
	v_add_u32_e32 v197, 0xffffffe4, v0
	v_cmp_gt_u32_e32 vcc, s34, v196
	v_cmp_gt_u32_e64 s[46:47], s34, v197
	v_cvt_f32_i32_e32 v196, v196
	v_cvt_f32_i32_e32 v197, v197
	v_fma_f32 v40, -v189, v196, v40
	v_fma_f32 v41, -v189, v197, v41
	v_cndmask_b32_e32 v40, v184, v40, vcc
	v_cndmask_b32_e64 v41, v184, v41, s[46:47]
	v_add_u32_e32 v196, 0xffffffc0, v0
	v_add_u32_e32 v197, 0xffffffbc, v0
	v_cmp_gt_u32_e32 vcc, s34, v196
	v_cmp_gt_u32_e64 s[46:47], s34, v197
	v_cvt_f32_i32_e32 v196, v196
	v_cvt_f32_i32_e32 v197, v197
	v_fma_f32 v42, -v189, v196, v42
	v_fma_f32 v43, -v189, v197, v43
	v_cndmask_b32_e32 v42, v184, v42, vcc
	v_cndmask_b32_e64 v43, v184, v43, s[46:47]
	v_add_u32_e32 v196, 0xffffffb8, v0
	v_add_u32_e32 v197, 0xffffffb4, v0
	v_cmp_gt_u32_e32 vcc, s34, v196
	v_cmp_gt_u32_e64 s[46:47], s34, v197
	v_cvt_f32_i32_e32 v196, v196
	v_cvt_f32_i32_e32 v197, v197
	v_fma_f32 v44, -v189, v196, v44
	v_fma_f32 v45, -v189, v197, v45
	v_cndmask_b32_e32 v44, v184, v44, vcc
	v_cndmask_b32_e64 v45, v184, v45, s[46:47]
	v_add_u32_e32 v196, 0xffffffb0, v0
	v_add_u32_e32 v197, 0xffffffac, v0
	v_cmp_gt_u32_e32 vcc, s34, v196
	v_cmp_gt_u32_e64 s[46:47], s34, v197
	v_cvt_f32_i32_e32 v196, v196
	v_cvt_f32_i32_e32 v197, v197
	v_fma_f32 v46, -v189, v196, v46
	v_fma_f32 v47, -v189, v197, v47
	v_cndmask_b32_e32 v46, v184, v46, vcc
	v_cndmask_b32_e64 v47, v184, v47, s[46:47]
	v_add_u32_e32 v196, 0xffffffa8, v0
	v_add_u32_e32 v197, 0xffffffa4, v0
	v_cmp_gt_u32_e32 vcc, s34, v196
	v_cmp_gt_u32_e64 s[46:47], s34, v197
	v_cvt_f32_i32_e32 v196, v196
	v_cvt_f32_i32_e32 v197, v197
	v_fma_f32 v48, -v189, v196, v48
	v_fma_f32 v49, -v189, v197, v49
	v_cndmask_b32_e32 v48, v184, v48, vcc
	v_cndmask_b32_e64 v49, v184, v49, s[46:47]
	v_max3_f32 v0, v34, s35, v35
	v_max3_f32 v0, v0, v36, v37
	v_max3_f32 v0, v0, v38, v39
	v_mbcnt_hi_u32_b32 v114, -1, v180
	v_max3_f32 v0, v0, v40, v41
	v_and_b32_e32 v116, 64, v114
	v_max3_f32 v0, v0, v42, v43
	v_xor_b32_e32 v115, 32, v114
	v_add_u32_e32 v116, 64, v116
	v_max3_f32 v0, v0, v44, v45
	v_cmp_lt_i32_e32 vcc, v115, v116
	v_max3_f32 v0, v0, v46, v47
	v_max3_f32 v0, v0, v48, v49
	v_cndmask_b32_e32 v114, v114, v115, vcc
	v_lshlrev_b32_e32 v114, 2, v114
	ds_bpermute_b32 v114, v114, v0
	s_waitcnt lgkmcnt(0)
	v_max3_f32 v191, v131, v0, v114
	v_cmp_neq_f32_e32 vcc, s35, v191
	s_nop 1
	v_cndmask_b32_e32 v114, 0, v191, vcc
	v_sub_f32_e32 v0, v131, v114
	v_mul_f32_e32 v0, 0x3fb8aa3b, v0
	v_exp_f32_e32 v0, v0
	s_nop 0
	v_cmp_neq_f32_e32 vcc, 1.0, v0
	s_cbranch_vccz .LBB0_798
	v_mul_f32_e32 v32, v32, v0
	v_mul_f32_e32 v33, v33, v0
	v_mul_f32_e32 v30, v30, v0
	v_mul_f32_e32 v31, v31, v0
	v_mul_f32_e32 v28, v28, v0
	v_mul_f32_e32 v29, v29, v0
	v_mul_f32_e32 v26, v26, v0
	v_mul_f32_e32 v27, v27, v0
	v_mul_f32_e32 v24, v24, v0
	v_mul_f32_e32 v25, v25, v0
	v_mul_f32_e32 v22, v22, v0
	v_mul_f32_e32 v23, v23, v0
	v_mul_f32_e32 v20, v20, v0
	v_mul_f32_e32 v21, v21, v0
	v_mul_f32_e32 v18, v18, v0
	v_mul_f32_e32 v19, v19, v0
	v_mul_f32_e32 v16, v16, v0
	v_mul_f32_e32 v17, v17, v0
	v_mul_f32_e32 v14, v14, v0
	v_mul_f32_e32 v15, v15, v0
	v_mul_f32_e32 v12, v12, v0
	v_mul_f32_e32 v13, v13, v0
	v_mul_f32_e32 v10, v10, v0
	v_mul_f32_e32 v11, v11, v0
	v_mul_f32_e32 v8, v8, v0
	v_mul_f32_e32 v9, v9, v0
	v_mul_f32_e32 v6, v6, v0
	v_mul_f32_e32 v7, v7, v0
	v_mul_f32_e32 v4, v4, v0
	v_mul_f32_e32 v5, v5, v0
	v_mul_f32_e32 v2, v2, v0
	v_mul_f32_e32 v3, v3, v0

; #define NEG_INF (-__builtin_inff())
; DI void softmax_step(float (&sc)[16], AState& st, const KV& kv) {
;   float mx = NEG_INF;
; #pragma unroll
;   for (int i = 0; i < 16; ++i) mx = fmaxf(mx, sc[i]);
;   mx = fmaxf(mx, __shfl_xor(mx, 32));
;   const float mnew = fmaxf(st.m, mx);
;   const float meff = (mnew == NEG_INF) ? 0.f : mnew;
;   const float alpha = __expf(st.m - meff);
;   float rs = 0.f;
; #pragma unroll
;   for (int i = 0; i < 16; ++i) { sc[i] = __expf(sc[i] - meff); rs += sc[i]; }
;   st.l = st.l * alpha + rs;
;   st.m = mnew;
;   if (__any(alpha != 1.f)) {
; #pragma unroll
;     for (int i = 0; i < 16; ++i) { st.o0[i] *= alpha; st.o1[i] *= alpha; }
; DI void band_tile(const KV& kv, const bf16x8 (&q)[4], AState& st, const Fam& f, int n0, int tq, int wtok, float nslope) {
;   const int h2 = (TIDX & 63) >> 5;
;   f32x16 s = qk_tile(kv, q);
;   float sc[16];
;   const int nb = n0 + 8 * h2;
; #pragma unroll
;   for (int i = 0; i < 16; ++i) {
;     const int n = nb + (i & 7) + 16 * (i >> 3);
;     const int stok = n * f.kstride + f.koff;
;     const int dist = tq - stok;
;     const bool valid = (stok >= 0) && (dist >= 0) && (dist <= wtok);
;     sc[i] = valid ? s[i] + nslope * (float)dist : NEG_INF;
;   }
;   softmax_step(sc, st, kv);
; }
.LBB0_804:
	v_mfma_f32_32x32x16_bf16 v[66:81], v[66:69], v[82:85], 0
	v_mov_b32_e32 v0, v159
	s_cmp_gt_i32 s10, -1
	v_lshrrev_b32_e32 v0, 2, v0
	s_cselect_b64 s[46:47], -1, 0
	s_movk_i32 s14, 0xffef
	v_mfma_f32_32x32x16_bf16 v[66:81], v[146:149], v[86:89], v[66:81]
	v_and_b32_e32 v146, 8, v0
	v_add_u32_e32 v147, s12, v192
	v_sub_u32_e32 v146, v147, v146
	v_mfma_f32_32x32x16_bf16 v[66:81], v[150:153], v[90:93], v[66:81]
	v_mfma_f32_32x32x16_bf16 v[66:81], v[154:157], v[94:97], v[66:81]
	s_nop 11
	v_mov_b32_e32 v196, v146
	v_add_u32_e32 v197, -1, v146
	v_cmp_gt_u32_e32 vcc, s9, v196
	v_cmp_gt_u32_e64 s[46:47], s9, v197
	v_cvt_f32_i32_e32 v196, v196
	v_cvt_f32_i32_e32 v197, v197
	v_fma_f32 v66, -v189, v196, v66
	v_fma_f32 v67, -v189, v197, v67
	v_cndmask_b32_e32 v66, v184, v66, vcc
	v_cndmask_b32_e64 v67, v184, v67, s[46:47]
	v_add_u32_e32 v196, -2, v146
	v_add_u32_e32 v197, -3, v146
	v_cmp_gt_u32_e32 vcc, s9, v196
	v_cmp_gt_u32_e64 s[46:47], s9, v197
	v_cvt_f32_i32_e32 v196, v196
	v_cvt_f32_i32_e32 v197, v197
	v_fma_f32 v68, -v189, v196, v68
	v_fma_f32 v69, -v189, v197, v69
	v_cndmask_b32_e32 v68, v184, v68, vcc
	v_cndmask_b32_e64 v69, v184, v69, s[46:47]
	v_add_u32_e32 v196, -4, v146
	v_add_u32_e32 v197, -5, v146
	v_cmp_gt_u32_e32 vcc, s9, v196
	v_cmp_gt_u32_e64 s[46:47], s9, v197
	v_cvt_f32_i32_e32 v196, v196
	v_cvt_f32_i32_e32 v197, v197
	v_fma_f32 v70, -v189, v196, v70
	v_fma_f32 v71, -v189, v197, v71
	v_cndmask_b32_e32 v70, v184, v70, vcc
	v_cndmask_b32_e64 v71, v184, v71, s[46:47]
	v_add_u32_e32 v196, -6, v146
	v_add_u32_e32 v197, -7, v146
	v_cmp_gt_u32_e32 vcc, s9, v196
	v_cmp_gt_u32_e64 s[46:47], s9, v197
	v_cvt_f32_i32_e32 v196, v196
	v_cvt_f32_i32_e32 v197, v197
	v_fma_f32 v72, -v189, v196, v72
	v_fma_f32 v73, -v189, v197, v73
	v_cndmask_b32_e32 v72, v184, v72, vcc
	v_cndmask_b32_e64 v73, v184, v73, s[46:47]
	v_add_u32_e32 v196, -16, v146
	v_add_u32_e32 v197, 0xffffffef, v146
	v_cmp_gt_u32_e32 vcc, s9, v196
	v_cmp_gt_u32_e64 s[46:47], s9, v197
	v_cvt_f32_i32_e32 v196, v196
	v_cvt_f32_i32_e32 v197, v197
	v_fma_f32 v74, -v189, v196, v74
	v_fma_f32 v75, -v189, v197, v75
	v_cndmask_b32_e32 v74, v184, v74, vcc
	v_cndmask_b32_e64 v75, v184, v75, s[46:47]
	v_add_u32_e32 v196, 0xffffffee, v146
	v_add_u32_e32 v197, 0xffffffed, v146
	v_cmp_gt_u32_e32 vcc, s9, v196
	v_cmp_gt_u32_e64 s[46:47], s9, v197
	v_cvt_f32_i32_e32 v196, v196
	v_cvt_f32_i32_e32 v197, v197
	v_fma_f32 v76, -v189, v196, v76
	v_fma_f32 v77, -v189, v197, v77
	v_cndmask_b32_e32 v76, v184, v76, vcc
	v_cndmask_b32_e64 v77, v184, v77, s[46:47]
	v_add_u32_e32 v196, 0xffffffec, v146
	v_add_u32_e32 v197, 0xffffffeb, v146
	v_cmp_gt_u32_e32 vcc, s9, v196
	v_cmp_gt_u32_e64 s[46:47], s9, v197
	v_cvt_f32_i32_e32 v196, v196
	v_cvt_f32_i32_e32 v197, v197
	v_fma_f32 v78, -v189, v196, v78
	v_fma_f32 v147, -v189, v197, v79
	v_cndmask_b32_e32 v78, v184, v78, vcc
	v_cndmask_b32_e64 v147, v184, v147, s[46:47]
	v_add_u32_e32 v196, 0xffffffea, v146
	v_add_u32_e32 v197, 0xffffffe9, v146
	v_cmp_gt_u32_e32 vcc, s9, v196
	v_cmp_gt_u32_e64 s[46:47], s9, v197
	v_cvt_f32_i32_e32 v196, v196
	v_cvt_f32_i32_e32 v197, v197
	v_fma_f32 v148, -v189, v196, v80
	v_fma_f32 v149, -v189, v197, v81
	v_cndmask_b32_e32 v148, v184, v148, vcc
	v_cndmask_b32_e64 v149, v184, v149, s[46:47]
	v_mbcnt_hi_u32_b32 v79, -1, v180
	v_max3_f32 v0, v66, s35, v67
	v_max3_f32 v0, v0, v68, v69
	v_max3_f32 v0, v0, v70, v71
	v_max3_f32 v0, v0, v72, v73
	v_and_b32_e32 v81, 64, v79
	v_max3_f32 v0, v0, v74, v75
	v_xor_b32_e32 v80, 32, v79
	v_add_u32_e32 v81, 64, v81
	v_max3_f32 v0, v0, v76, v77
	v_cmp_lt_i32_e32 vcc, v80, v81
	v_max3_f32 v0, v0, v78, v147
	v_max3_f32 v0, v0, v148, v149
	v_cndmask_b32_e32 v146, v79, v80, vcc
	v_lshlrev_b32_e32 v146, 2, v146
	ds_bpermute_b32 v146, v146, v0
	s_waitcnt lgkmcnt(0)
	v_max3_f32 v146, v191, v0, v146
	v_cmp_neq_f32_e32 vcc, s35, v146
	s_nop 1
	v_cndmask_b32_e32 v150, 0, v146, vcc
	v_sub_f32_e32 v0, v191, v150
	v_mul_f32_e32 v0, 0x3fb8aa3b, v0
	v_exp_f32_e32 v0, v0
	s_nop 0
	v_cmp_neq_f32_e32 vcc, 1.0, v0
	s_cbranch_vccz .LBB0_806
	v_mul_f32_e32 v64, v64, v0
	v_mul_f32_e32 v65, v65, v0
	v_mul_f32_e32 v62, v62, v0
	v_mul_f32_e32 v63, v63, v0
	v_mul_f32_e32 v60, v60, v0
	v_mul_f32_e32 v61, v61, v0
	v_mul_f32_e32 v58, v58, v0
	v_mul_f32_e32 v59, v59, v0
	v_mul_f32_e32 v56, v56, v0
	v_mul_f32_e32 v57, v57, v0
	v_mul_f32_e32 v54, v54, v0
	v_mul_f32_e32 v55, v55, v0
	v_mul_f32_e32 v52, v52, v0
	v_mul_f32_e32 v53, v53, v0
	v_mul_f32_e32 v50, v50, v0
	v_mul_f32_e32 v51, v51, v0
	v_mul_f32_e32 v48, v48, v0
	v_mul_f32_e32 v49, v49, v0
	v_mul_f32_e32 v46, v46, v0
	v_mul_f32_e32 v47, v47, v0
	v_mul_f32_e32 v44, v44, v0
	v_mul_f32_e32 v45, v45, v0
	v_mul_f32_e32 v42, v42, v0
	v_mul_f32_e32 v43, v43, v0
	v_mul_f32_e32 v40, v40, v0
	v_mul_f32_e32 v41, v41, v0
	v_mul_f32_e32 v38, v38, v0
	v_mul_f32_e32 v39, v39, v0
	v_mul_f32_e32 v36, v36, v0
	v_mul_f32_e32 v37, v37, v0
	v_mul_f32_e32 v34, v34, v0
	v_mul_f32_e32 v35, v35, v0

; DI void cmp_item(const u16* R, const u16* kc, const u16* vct, float* Oc, float* impH, float* linv, int hh, int qtile, float kcmax2, int part, float* lds) {
;     ...
;       const float g0 = p[0] + p[1] + p[2] + p[3], g1 = p[4] + p[5] + p[6] + p[7];
;       const float g2 = p[8] + p[9] + p[10] + p[11], g3 = p[12] + p[13] + p[14] + p[15];
;       l += (g0 + g1) + (g2 + g3);
;       const float xp7 = __shfl_xor(p[7], 32), xp15 = __shfl_xor(p[15], 32);
;       const int gb = (n0 >> 2) + 2 * h2;
;       f32x2 w0 = {g0 + (h2 ? xp7 : carryE), g1 + p[3]};
;       f32x2 w1 = {g2 + (h2 ? xp15 : xp7), g3 + p[11]};
;       *reinterpret_cast<f32x2*>(imp_row + gb) = w0;
;       *reinterpret_cast<f32x2*>(imp_row + gb + 4) = w1;
;       carryE = xp15;
;       pv_tile(cur, p, st);
;       cur = nxt;
.LBB0_872:
	s_or_b64 exec, exec, s[52:53]
	v_add_u32_e32 v40, 0x170, v146
	v_cvt_f32_i32_e32 v40, v40
	v_add_u32_e32 v0, 0xffffff00, v147
	s_and_b64 s[10:11], exec, s[44:45]
	v_cmp_le_i32_e64 s[44:45], v0, v126
	v_add_f32_e32 v40, 0xc1780000, v40
	v_fma_f32 v34, -v140, v40, v34
	v_sub_f32_e32 v34, v34, v141
	v_mul_f32_e32 v34, 0x3fb8aa3b, v34
	v_exp_f32_e32 v34, v34
	v_add_f32_e32 v42, v120, v36
	v_add_f32_e32 v43, v121, v37
	ds_bpermute_b32 v48, v138, v39
	v_add_f32_e32 v42, v42, v122
	v_add_f32_e32 v43, v43, v123
	v_cndmask_b32_e64 v34, 0, v34, s[44:45]
	v_add_f32_e32 v40, v34, v116
	v_add_f32_e32 v41, v35, v117
	v_add_f32_e32 v42, v42, v38
	v_add_f32_e32 v43, v43, v39
	v_add_f32_e32 v40, v40, v118
	v_add_f32_e32 v41, v41, v119
	v_mov_b32_e32 v47, v42
	v_add_f32_e32 v40, v40, v114
	v_add_f32_e32 v41, v41, v115
	s_or_b64 s[50:51], s[10:11], s[50:51]
	v_add_f32_e32 v44, v40, v42
	v_add_f32_e32 v45, v41, v43
	v_mov_b32_e32 v46, v40
	v_add_f32_e32 v0, v44, v45
	v_add_f32_e32 v145, v145, v0
	ds_bpermute_b32 v0, v138, v38
	v_mov_b32_e32 v45, v114
	v_mov_b32_e32 v42, v41
	v_mov_b32_e32 v41, v115
	v_add_u32_e32 v146, 0xfffffe00, v146
	s_waitcnt lgkmcnt(0)
	v_cndmask_b32_e32 v44, v0, v137, vcc
	v_cndmask_b32_e32 v40, v48, v0, vcc
	v_ashrrev_i32_e32 v137, 31, v136
	v_add_f32_e32 v44, v46, v44
	v_add_f32_e32 v45, v47, v45
	v_add_f32_e32 v40, v42, v40
	v_add_f32_e32 v41, v43, v41
	v_lshl_add_u64 v[42:43], v[136:137], 2, v[132:133]
	global_store_dwordx2 v[42:43], v[44:45], off
	global_store_dwordx2 v[42:43], v[40:41], off offset:16
	v_cvt_pk_bf16_f32 v40, v34, v116
	v_cvt_pk_bf16_f32 v41, v118, v114
	v_cvt_pk_bf16_f32 v42, v120, v36
	v_cvt_pk_bf16_f32 v43, v122, v38
	v_cvt_pk_bf16_f32 v34, v35, v117
	v_cvt_pk_bf16_f32 v35, v119, v115
	v_mfma_f32_32x32x16_bf16 v[18:33], v[78:81], v[40:43], v[18:33]
	v_cvt_pk_bf16_f32 v36, v121, v37
	v_cvt_pk_bf16_f32 v37, v123, v39
	s_waitcnt vmcnt(8)
	v_mov_b64_e32 v[116:117], v[108:109]
	s_waitcnt vmcnt(7)
	v_mov_b64_e32 v[124:125], v[104:105]
	s_waitcnt vmcnt(6)
	v_mov_b64_e32 v[120:121], v[100:101]
	s_waitcnt vmcnt(5)
	v_mov_b64_e32 v[78:79], v[86:87]
	v_add_u32_e32 v147, 0x200, v147
	v_mfma_f32_32x32x16_bf16 v[2:17], v[70:73], v[40:43], v[2:17]
	s_waitcnt vmcnt(3)
	v_mov_b64_e32 v[70:71], v[94:95]
	v_add_u32_e32 v136, 8, v136
	v_add_u32_e32 v148, 32, v148
	v_mov_b32_e32 v137, v48
	v_mov_b64_e32 v[114:115], v[106:107]
	v_mov_b64_e32 v[122:123], v[102:103]
	v_mov_b64_e32 v[118:119], v[98:99]
	v_mfma_f32_32x32x16_bf16 v[18:33], v[74:77], v[34:37], v[18:33]
	v_mov_b64_e32 v[74:75], v[82:83]
	v_mov_b64_e32 v[80:81], v[88:89]
	v_mov_b64_e32 v[76:77], v[84:85]
	v_mov_b64_e32 v[72:73], v[96:97]
	v_mfma_f32_32x32x16_bf16 v[2:17], v[66:69], v[34:37], v[2:17]
	v_mov_b64_e32 v[34:35], v[110:111]
	s_waitcnt vmcnt(2)
	v_mov_b64_e32 v[66:67], v[90:91]
	v_mov_b64_e32 v[36:37], v[112:113]
	v_mov_b64_e32 v[68:69], v[92:93]
	s_andn2_b64 exec, exec, s[50:51]
	s_cbranch_execz .LBB0_905

; DI void cmp_item(const u16* R, const u16* kc, const u16* vct, float* Oc, float* impH, float* linv, int hh, int qtile, float kcmax2, int part, float* lds) {
;     ...
;   if (part == 0) {
;     l += my[64 + lane];
; #pragma unroll
;     for (int i = 0; i < 16; ++i) { st.o0[i] += my[(2 + i) * 64 + lane]; st.o1[i] += my[(18 + i) * 64 + lane]; }
;     const float lt = l + __shfl_xor(l, 32);
;     const float inv = 1.f / fmaxf(lt, 1e-30f);
;     if (h2 == 0) linv[(size_t)hh * SEQ + tq] = inv;
;     float* orow = Oc + (size_t)tq * 256 + hh * 64;
; #pragma unroll
;     for (int g = 0; g < 4; ++g) {
;       f32x4 a = {st.o0[4 * g] * inv, st.o0[4 * g + 1] * inv, st.o0[4 * g + 2] * inv, st.o0[4 * g + 3] * inv};
;       f32x4 b = {st.o1[4 * g] * inv, st.o1[4 * g + 1] * inv, st.o1[4 * g + 2] * inv, st.o1[4 * g + 3] * inv};
;       *reinterpret_cast<f32x4*>(orow + 8 * g + 4 * h2) = a;
;       *reinterpret_cast<f32x4*>(orow + 32 + 8 * g + 4 * h2) = b;
;     }
.LBB0_911:
	s_or_b64 exec, exec, s[46:47]
	v_mov_b32_e32 v68, v35
	v_mov_b32_e32 v69, v50
	v_add_f32_e32 v18, v18, v68
	v_add_f32_e32 v19, v19, v69
	v_mov_b32_e32 v68, v37
	v_mov_b32_e32 v69, v60
	v_add_f32_e32 v68, v2, v68
	v_add_f32_e32 v69, v3, v69
	v_mov_b32_e32 v2, v51
	v_mov_b32_e32 v3, v48
	v_add_f32_e32 v20, v20, v2
	v_add_f32_e32 v21, v21, v3
	v_mov_b32_e32 v2, v61
	v_mov_b32_e32 v3, v54
	v_add_f32_e32 v50, v4, v2
	v_add_f32_e32 v51, v5, v3
	v_mov_b32_e32 v2, v49
	v_mov_b32_e32 v3, v40
	v_add_f32_e32 v22, v22, v2
	v_add_f32_e32 v23, v23, v3
	v_mov_b32_e32 v2, v55
	v_mov_b32_e32 v3, v44
	v_add_f32_e32 v48, v6, v2
	v_add_f32_e32 v49, v7, v3
	v_mov_b32_e32 v2, v41
	s_waitcnt lgkmcnt(8)
	v_mov_b32_e32 v3, v64
	v_add_f32_e32 v24, v24, v2
	v_add_f32_e32 v25, v25, v3
	v_mov_b32_e32 v2, v45
	s_waitcnt lgkmcnt(4)
	v_mov_b32_e32 v3, v66
	v_add_f32_e32 v40, v8, v2
	v_add_f32_e32 v41, v9, v3
	v_mov_b32_e32 v2, v65
	v_mov_b32_e32 v3, v58
	v_add_f32_e32 v26, v26, v2
	v_add_f32_e32 v27, v27, v3
	v_mov_b32_e32 v2, v67
	s_waitcnt lgkmcnt(3)
	v_mov_b32_e32 v3, v62
	v_add_f32_e32 v10, v10, v2
	v_add_f32_e32 v11, v11, v3
	v_mov_b32_e32 v2, v59
	v_mov_b32_e32 v3, v52
	v_add_f32_e32 v28, v28, v2
	v_add_f32_e32 v29, v29, v3
	v_mov_b32_e32 v2, v63
	s_waitcnt lgkmcnt(2)
	v_mov_b32_e32 v3, v56
	v_add_f32_e32 v12, v12, v2
	v_add_f32_e32 v13, v13, v3
	v_mov_b32_e32 v2, v53
	v_mov_b32_e32 v3, v38
	v_add_f32_e32 v30, v30, v2
	v_add_f32_e32 v31, v31, v3
	v_mov_b32_e32 v2, v57
	s_waitcnt lgkmcnt(1)
	v_mov_b32_e32 v3, v46
	v_add_f32_e32 v14, v14, v2
	v_add_f32_e32 v15, v15, v3
	v_mov_b32_e32 v2, v39
	v_mov_b32_e32 v3, v36
	v_readlane_b32 s10, v252, 58
	v_add_f32_e32 v32, v32, v2
	v_add_f32_e32 v33, v33, v3
	v_lshlrev_b64 v[2:3], 10, v[126:127]
	v_readlane_b32 s11, v252, 59
	s_lshl_b32 s2, s55, 2
	v_lshlrev_b32_e32 v0, 4, v139
	v_lshl_add_u64 v[2:3], s[10:11], 0, v[2:3]
	v_lshl_add_u64 v[2:3], v[2:3], 0, s[2:3]
	v_lshl_add_u64 v[36:37], v[2:3], 0, v[0:1]
	v_mul_f32_e32 v2, v18, v34
	v_mul_f32_e32 v3, v19, v34
	v_mul_f32_e32 v4, v20, v34
	v_mul_f32_e32 v5, v21, v34
	v_mul_f32_e32 v6, v68, v34
	v_mul_f32_e32 v7, v69, v34
	v_mul_f32_e32 v8, v50, v34
	v_mul_f32_e32 v9, v51, v34
	global_store_dwordx4 v[36:37], v[2:5], off
	global_store_dwordx4 v[36:37], v[6:9], off offset:128
	v_mov_b32_e32 v42, v47
	v_mul_f32_e32 v2, v22, v34
	v_mul_f32_e32 v3, v23, v34
	v_mul_f32_e32 v4, v24, v34
	v_mul_f32_e32 v5, v25, v34
	v_mul_f32_e32 v6, v48, v34
	v_mul_f32_e32 v7, v49, v34
	v_mul_f32_e32 v8, v40, v34
	v_mul_f32_e32 v9, v41, v34
	global_store_dwordx4 v[36:37], v[2:5], off offset:32
	global_store_dwordx4 v[36:37], v[6:9], off offset:160
	s_waitcnt lgkmcnt(0)
	v_add_f32_e32 v16, v16, v42
	v_add_f32_e32 v17, v17, v43
	v_mul_f32_e32 v2, v26, v34
	v_mul_f32_e32 v3, v27, v34
	v_mul_f32_e32 v4, v28, v34
	v_mul_f32_e32 v5, v29, v34
	v_mul_f32_e32 v6, v10, v34
	v_mul_f32_e32 v7, v11, v34
	v_mul_f32_e32 v8, v12, v34
	v_mul_f32_e32 v9, v13, v34
	global_store_dwordx4 v[36:37], v[2:5], off offset:64
	global_store_dwordx4 v[36:37], v[6:9], off offset:192
	s_nop 0
	v_mul_f32_e32 v2, v30, v34
	v_mul_f32_e32 v3, v31, v34
	v_mul_f32_e32 v4, v32, v34
	v_mul_f32_e32 v5, v33, v34
	v_mul_f32_e32 v6, v14, v34
	v_mul_f32_e32 v7, v15, v34
	v_mul_f32_e32 v8, v16, v34
	v_mul_f32_e32 v9, v17, v34
	global_store_dwordx4 v[36:37], v[2:5], off offset:96
	global_store_dwordx4 v[36:37], v[6:9], off offset:224

; #define NEG_INF (-__builtin_inff())
; DI float bf2f(u16 v) { return __uint_as_float((u32)v << 16); }
; DI float sigmoidf_(float x) { return 1.f / (1.f + __expf(-x)); }
; DI void nsa_group(const u16* R, const u16* T, const float* Oc, const float* Ow, const u32* selm, const float* bg, const float* gh, u16* obuf, int qtile, char* lds) {
;     ...
;   __syncthreads();
;   if (part == 0) {
;     const float m1 = my[lane], l1 = my[64 + lane];
;     const float mm = fmaxf(st.m, m1);
;     const float a0_ = (st.m == NEG_INF) ? 0.f : __expf(st.m - mm), a1_ = (m1 == NEG_INF) ? 0.f : __expf(m1 - mm);
;     st.l = st.l * a0_ + l1 * a1_;
; #pragma unroll
;     for (int i = 0; i < 16; ++i) {
;       st.o0[i] = st.o0[i] * a0_ + my[(2 + i) * 64 + lane] * a1_;
;       st.o1[i] = st.o1[i] * a0_ + my[(18 + i) * 64 + lane] * a1_;
;     }
;     state_finish(st);
;     const float gc = sigmoidf_(bf2f(R[(size_t)tq * LDR + RC_GATE + 0 + hh]) + bg[0 + hh]);
;     const float gs = sigmoidf_(bf2f(R[(size_t)tq * LDR + RC_GATE + 4 + hh]) + bg[4 + hh]);
;     const float gw = sigmoidf_(bf2f(R[(size_t)tq * LDR + RC_GATE + 8 + hh]) + bg[8 + hh]);
;     f32x16 a0, a1;
;     const float* orow = Oc + (size_t)tq * 256 + hh * 64;
;     const float* wrow = Ow + (size_t)tq * 256 + hh * 64;
; #pragma unroll
;     for (int g = 0; g < 4; ++g) {
;       f32x4 a = *reinterpret_cast<const f32x4*>(orow + 8 * g + 4 * h2);
;       f32x4 b = *reinterpret_cast<const f32x4*>(orow + 32 + 8 * g + 4 * h2);
;       f32x4 wa = *reinterpret_cast<const f32x4*>(wrow + 8 * g + 4 * h2);
;       f32x4 wb = *reinterpret_cast<const f32x4*>(wrow + 32 + 8 * g + 4 * h2);
.LBB0_1118:
	s_cmpk_gt_u32 s79, 0xff
	s_waitcnt lgkmcnt(0)
	s_barrier
	s_cbranch_scc1 .LBB0_865
	s_lshl_b32 s2, s73, 1
	v_lshl_add_u64 v[2:3], v[90:91], 0, s[2:3]
	s_movk_i32 s2, 0x1000
	v_add_co_u32_e32 v2, vcc, s2, v2
	s_lshl_b32 s2, s73, 2
	s_nop 0
	v_addc_co_u32_e32 v3, vcc, 0, v3, vcc
	global_load_ushort v84, v[2:3], off
	v_mov_b32_e32 v4, s2
	global_load_dword v85, v4, s[26:27]
	global_load_ushort v92, v[2:3], off offset:8
	s_lshl_b32 s2, s78, 2
	v_mov_b32_e32 v10, s2
	global_load_dword v93, v10, s[26:27] offset:16
	ds_read2st64_b32 v[4:5], v0 offset1:1
	s_waitcnt vmcnt(5)
	ds_read2st64_b32 v[72:73], v0 offset0:2 offset1:3
	ds_read2st64_b32 v[74:75], v0 offset0:4 offset1:5
	ds_read2st64_b32 v[68:69], v0 offset0:6 offset1:7
	ds_read2st64_b32 v[70:71], v0 offset0:8 offset1:9
	ds_read2st64_b32 v[64:65], v0 offset0:10 offset1:11
	ds_read2st64_b32 v[90:91], v0 offset0:12 offset1:13
	ds_read2st64_b32 v[82:83], v0 offset0:14 offset1:15
	ds_read2st64_b32 v[58:59], v0 offset0:24 offset1:25
	ds_read2st64_b32 v[14:15], v0 offset0:26 offset1:27
	s_waitcnt vmcnt(4)
	ds_read2st64_b32 v[86:87], v0 offset0:28 offset1:29
	ds_read2st64_b32 v[80:81], v0 offset0:30 offset1:31
	ds_read2st64_b32 v[60:61], v0 offset0:18 offset1:19
	ds_read2st64_b32 v[62:63], v0 offset0:20 offset1:21
	ds_read2st64_b32 v[56:57], v0 offset0:22 offset1:23
	ds_read2st64_b32 v[78:79], v0 offset0:16 offset1:17
	ds_read2st64_b32 v[76:77], v0 offset0:32 offset1:33
	global_load_ushort v106, v[2:3], off offset:16
	global_load_dword v107, v10, s[26:27] offset:32
	v_readlane_b32 s10, v252, 58
	v_lshlrev_b64 v[6:7], 10, v[88:89]
	v_readlane_b32 s11, v252, 59
	s_lshl_b32 s2, s72, 2
	v_lshlrev_b32_e32 v0, 4, v105
	v_lshl_add_u64 v[8:9], s[10:11], 0, v[6:7]
	v_readlane_b32 s10, v252, 60
	v_readlane_b32 s11, v252, 61
	v_lshl_add_u64 v[2:3], v[8:9], 0, s[2:3]
	v_max_f32_e32 v11, v129, v129
	v_lshl_add_u64 v[6:7], s[10:11], 0, v[6:7]
	v_lshl_add_u64 v[6:7], v[6:7], 0, s[2:3]
	v_lshl_add_u64 v[126:127], v[2:3], 0, v[0:1]
	v_lshl_add_u64 v[134:135], v[6:7], 0, v[0:1]
	s_waitcnt lgkmcnt(14)
	v_max_f32_e32 v0, v4, v4
	v_max_f32_e32 v0, v11, v0
	v_sub_f32_e32 v2, v129, v0
	v_sub_f32_e32 v0, v4, v0
	v_mul_f32_e32 v0, 0x3fb8aa3b, v0
	v_exp_f32_e32 v0, v0
	v_mul_f32_e32 v2, 0x3fb8aa3b, v2
	v_exp_f32_e32 v2, v2
	v_cmp_neq_f32_e32 vcc, s35, v4
	v_mov_b32_e32 v95, v5
	global_load_dwordx4 v[6:9], v[126:127], off offset:64
	global_load_dwordx4 v[52:55], v[126:127], off offset:96
	v_cndmask_b32_e32 v67, 0, v0, vcc
	v_cmp_neq_f32_e32 vcc, s35, v129
	v_mov_b32_e32 v142, v67
	s_waitcnt lgkmcnt(6)
	v_mul_f32_e32 v86, v142, v86
	v_mul_f32_e32 v87, v142, v87
	v_cndmask_b32_e32 v66, 0, v2, vcc
	v_mul_f32_e32 v2, v94, v66
	v_mul_f32_e32 v3, v95, v67
	v_mul_f32_e32 v90, v142, v90
	v_mul_f32_e32 v91, v142, v91
	v_add_f32_e32 v0, v2, v3
	ds_bpermute_b32 v10, v138, v0
	global_load_dwordx4 v[2:5], v[126:127], off offset:192
	global_load_dwordx4 v[94:97], v[126:127], off offset:224
	global_load_dwordx4 v[48:51], v[134:135], off offset:64
	global_load_dwordx4 v[98:101], v[134:135], off offset:96
	v_fma_f32 v26, v26, v66, v86
	v_fma_f32 v27, v27, v66, v87
	v_fma_f32 v42, v42, v66, v90
	v_fma_f32 v43, v43, v66, v91
	s_add_u32 s44, s21, s2
	s_waitcnt lgkmcnt(0)
	v_add_f32_e32 v0, v0, v10
	v_max_f32_e32 v0, 0xda24260, v0
	v_div_scale_f32 v108, s[10:11], v0, v0, 1.0
	v_rcp_f32_e32 v109, v108
	v_div_scale_f32 v110, vcc, 1.0, v0, 1.0
	global_load_dwordx4 v[10:13], v[134:135], off offset:192
	global_load_dwordx4 v[102:105], v[134:135], off offset:224
	v_fma_f32 v111, -v108, v109, 1.0
	v_fmac_f32_e32 v109, v111, v109
	v_mul_f32_e32 v111, v110, v109
	v_fma_f32 v112, -v108, v111, v110
	v_fmac_f32_e32 v111, v112, v109
	v_fma_f32 v108, -v108, v111, v110
	v_div_fmas_f32 v108, v108, v109, v111
	v_div_fixup_f32 v0, v108, v0, 1.0
	v_mul_f32_e32 v86, v26, v0
	v_mul_f32_e32 v87, v27, v0
	v_mul_f32_e32 v42, v42, v0
	v_mul_f32_e32 v43, v43, v0
	s_addc_u32 s45, s22, 0
	v_mul_f32_e32 v58, v142, v58
	v_mul_f32_e32 v59, v142, v59
	v_mul_f32_e32 v14, v142, v14
	v_mul_f32_e32 v15, v142, v15
	s_lshl_b32 s2, s72, 1
	s_waitcnt vmcnt(13)
	v_lshlrev_b32_e32 v84, 16, v84
	s_waitcnt vmcnt(12)
	v_add_f32_e32 v84, v85, v84
	v_mul_f32_e32 v84, 0xbfb8aa3b, v84
	v_exp_f32_e32 v84, v84
	s_waitcnt vmcnt(11)
	v_lshlrev_b32_e32 v85, 16, v92
	s_waitcnt vmcnt(10)
	v_add_f32_e32 v85, v93, v85
	v_mul_f32_e32 v85, 0xbfb8aa3b, v85
	v_add_f32_e32 v84, 1.0, v84
	v_div_scale_f32 v92, s[10:11], v84, v84, 1.0
	v_rcp_f32_e32 v93, v92
	v_exp_f32_e32 v85, v85
	v_div_scale_f32 v108, vcc, 1.0, v84, 1.0
	v_fma_f32 v109, -v92, v93, 1.0
	v_fmac_f32_e32 v93, v109, v93
	v_add_f32_e32 v85, 1.0, v85
	s_waitcnt vmcnt(9)
	v_lshlrev_b32_e32 v106, 16, v106
	v_mul_f32_e32 v109, v108, v93
	v_div_scale_f32 v114, s[10:11], v85, v85, 1.0
	s_waitcnt vmcnt(8)
	v_add_f32_e32 v106, v107, v106
	v_fma_f32 v110, -v92, v109, v108
	v_rcp_f32_e32 v115, v114
	v_mul_f32_e32 v106, 0xbfb8aa3b, v106
	v_fmac_f32_e32 v109, v110, v93
	v_exp_f32_e32 v116, v106
	v_fma_f32 v92, -v92, v109, v108
	v_div_fmas_f32 v92, v92, v93, v109
	v_div_fixup_f32 v84, v92, v84, 1.0
	v_fma_f32 v92, -v114, v115, 1.0
	v_fmac_f32_e32 v115, v92, v115
	v_div_scale_f32 v92, vcc, 1.0, v85, 1.0
	v_add_f32_e32 v122, 1.0, v116
	v_mul_f32_e32 v93, v92, v115
	v_div_scale_f32 v123, s[10:11], v122, v122, 1.0
	v_fma_f32 v108, -v114, v93, v92
	v_rcp_f32_e32 v124, v123
	v_fmac_f32_e32 v93, v108, v115
	v_fma_f32 v92, -v114, v93, v92
	v_div_fmas_f32 v92, v92, v115, v93
	v_div_fixup_f32 v92, v92, v85, 1.0
	v_fma_f32 v85, -v123, v124, 1.0
	global_load_dwordx4 v[106:109], v[134:135], off
	global_load_dwordx4 v[110:113], v[126:127], off
	v_fmac_f32_e32 v124, v85, v124
	v_div_scale_f32 v85, vcc, 1.0, v122, 1.0
	global_load_dwordx4 v[114:117], v[134:135], off offset:32
	global_load_dwordx4 v[118:121], v[126:127], off offset:32
	v_mul_f32_e32 v93, v85, v124
	v_fma_f32 v125, -v123, v93, v85
	v_fmac_f32_e32 v93, v125, v124
	v_fma_f32 v85, -v123, v93, v85
	v_div_fmas_f32 v85, v85, v124, v93
	v_div_fixup_f32 v140, v85, v122, 1.0
	global_load_dwordx4 v[122:125], v[126:127], off offset:128
	s_nop 0
	global_load_dwordx4 v[126:129], v[126:127], off offset:160
	s_nop 0
	global_load_dwordx4 v[130:133], v[134:135], off offset:128
	s_nop 0
	global_load_dwordx4 v[134:137], v[134:135], off offset:160
	v_mov_b32_e32 v85, v159
	s_waitcnt vmcnt(11)
; DI void write_headnorm(const f32x16& o0, const f32x16& o1, const float* __restrict__ gh, u16* obuf, int tq, int colbase) {
;   const int h2 = (TIDX & 63) >> 5;
;   float ss = 0.f;
; #pragma unroll
;   for (int i = 0; i < 16; ++i) ss += o0[i] * o0[i] + o1[i] * o1[i];
;   ss += __shfl_xor(ss, 32);
; DI void nsa_group(const u16* R, const u16* T, const float* Oc, const float* Ow, const u32* selm, const float* bg, const float* gh, u16* obuf, int qtile, char* lds) {
;     ...
; #pragma unroll
;     for (int g = 0; g < 4; ++g) {
;       f32x4 a = *reinterpret_cast<const f32x4*>(orow + 8 * g + 4 * h2);
;       f32x4 b = *reinterpret_cast<const f32x4*>(orow + 32 + 8 * g + 4 * h2);
;       f32x4 wa = *reinterpret_cast<const f32x4*>(wrow + 8 * g + 4 * h2);
;       f32x4 wb = *reinterpret_cast<const f32x4*>(wrow + 32 + 8 * g + 4 * h2);
; #pragma unroll
;       for (int j = 0; j < 4; ++j) {
;         a0[4 * g + j] = gc * a[j] + gw * wa[j] + gs * st.o0[4 * g + j];
;         a1[4 * g + j] = gc * b[j] + gw * wb[j] + gs * st.o1[4 * g + j];
;       }
;     }
	v_mul_f32_e32 v26, v140, v50
	v_mul_f32_e32 v27, v140, v51
	s_waitcnt vmcnt(9)
	v_mul_f32_e32 v10, v140, v10
	v_mul_f32_e32 v11, v140, v11
	v_fma_f32 v8, v84, v8, v26
	v_fma_f32 v9, v84, v9, v27
	v_fma_f32 v26, v42, v92, v8
	v_fma_f32 v27, v43, v92, v9
	v_mul_f32_e32 v8, v140, v12
	v_mul_f32_e32 v9, v140, v13
	v_fma_f32 v4, v84, v4, v8
	v_fma_f32 v5, v84, v5, v9
	v_fma_f32 v4, v86, v92, v4
	v_fma_f32 v5, v87, v92, v5
	v_mul_f32_e32 v12, v142, v80
	v_mul_f32_e32 v13, v142, v81
	v_mul_f32_e32 v8, v4, v4
	v_mul_f32_e32 v9, v5, v5
	v_fma_f32 v12, v28, v66, v12
	v_fma_f32 v13, v29, v66, v13
	v_fma_f32 v42, v26, v26, v8
	v_fma_f32 v43, v27, v27, v9
	v_mul_f32_e32 v8, v142, v82
	v_mul_f32_e32 v9, v142, v83
	v_fma_f32 v8, v44, v66, v8
	v_fma_f32 v9, v45, v66, v9
	v_mul_f32_e32 v28, v12, v0
	v_mul_f32_e32 v29, v13, v0
	v_mul_f32_e32 v12, v140, v98
	v_mul_f32_e32 v13, v140, v99
	v_mul_f32_e32 v8, v8, v0
	v_mul_f32_e32 v9, v9, v0
	v_fma_f32 v12, v84, v52, v12
	v_fma_f32 v13, v84, v53, v13
	v_fma_f32 v12, v8, v92, v12
	v_fma_f32 v13, v9, v92, v13
	s_waitcnt vmcnt(8)
	v_mul_f32_e32 v8, v140, v102
	v_mul_f32_e32 v9, v140, v103
	v_fma_f32 v8, v84, v94, v8
	v_fma_f32 v9, v84, v95, v9
	v_fma_f32 v8, v28, v92, v8
	v_fma_f32 v9, v29, v92, v9
	v_lshrrev_b32_e32 v50, 3, v85
	v_mul_f32_e32 v28, v8, v8
	v_mul_f32_e32 v29, v9, v9
	v_readlane_b32 s10, v255, 39
	v_fma_f32 v44, v12, v12, v28
	v_fma_f32 v45, v13, v13, v29
	v_mul_f32_e32 v28, v142, v78
	v_mul_f32_e32 v29, v142, v79
	v_fma_f32 v28, v46, v66, v28
	v_fma_f32 v29, v47, v66, v29
	v_mul_f32_e32 v46, v142, v76
	v_mul_f32_e32 v47, v142, v77
	v_fma_f32 v30, v30, v66, v46
	v_fma_f32 v31, v31, v66, v47
	v_mul_f32_e32 v28, v28, v0
	v_mul_f32_e32 v29, v29, v0
	v_mul_f32_e32 v46, v30, v0
	v_mul_f32_e32 v47, v31, v0
	v_mul_f32_e32 v30, v140, v100
	v_mul_f32_e32 v31, v140, v101
	v_fma_f32 v30, v84, v54, v30
	v_fma_f32 v31, v84, v55, v31
	v_fma_f32 v30, v28, v92, v30
	v_fma_f32 v31, v29, v92, v31
	v_mul_f32_e32 v28, v140, v104
	v_mul_f32_e32 v29, v140, v105
	v_and_b32_e32 v67, 4, v50
	v_mul_f32_e32 v50, v142, v74
	v_mul_f32_e32 v51, v142, v75
	v_mul_f32_e32 v54, v142, v70
	v_mul_f32_e32 v55, v142, v71
	v_fma_f32 v28, v84, v96, v28
	v_fma_f32 v29, v84, v97, v29
	v_lshlrev_b32_e32 v85, 2, v67
	v_fma_f32 v34, v34, v66, v50
	v_fma_f32 v35, v35, v66, v51
	v_fma_f32 v38, v38, v66, v54
	v_fma_f32 v39, v39, v66, v55
	v_mul_f32_e32 v34, v34, v0
	v_mul_f32_e32 v35, v35, v0
	v_mul_f32_e32 v38, v38, v0
	v_mul_f32_e32 v39, v39, v0
	v_fma_f32 v22, v22, v66, v58
	v_fma_f32 v23, v23, v66, v59
	v_fma_f32 v14, v24, v66, v14
	v_fma_f32 v15, v25, v66, v15
	v_mul_f32_e32 v22, v22, v0
	v_mul_f32_e32 v23, v23, v0
	v_mul_f32_e32 v14, v14, v0
	v_mul_f32_e32 v15, v15, v0
	v_fma_f32 v2, v84, v2, v10
	v_fma_f32 v3, v84, v3, v11
	v_fma_f32 v2, v14, v92, v2
	v_fma_f32 v3, v15, v92, v3
	v_fma_f32 v28, v46, v92, v28
	v_fma_f32 v29, v47, v92, v29
	v_mul_f32_e32 v10, v2, v2
	v_mul_f32_e32 v11, v3, v3
	v_mul_f32_e32 v46, v28, v28
	v_mul_f32_e32 v47, v29, v29
	v_readlane_b32 s11, v255, 40
	v_fma_f32 v46, v30, v30, v46
	v_fma_f32 v47, v31, v31, v47
	s_waitcnt vmcnt(7)
	v_mul_f32_e32 v50, v108, v140
	v_mul_f32_e32 v51, v109, v140
	s_waitcnt vmcnt(6)
	v_fma_f32 v50, v84, v112, v50
	v_fma_f32 v51, v84, v113, v51
	v_fma_f32 v34, v34, v92, v50
	v_fma_f32 v35, v35, v92, v51
	v_mul_f32_e32 v50, v72, v142
	v_mul_f32_e32 v51, v73, v142
	s_waitcnt vmcnt(5)
	v_mul_f32_e32 v54, v140, v116
	v_mul_f32_e32 v55, v140, v117
	s_waitcnt vmcnt(4)
	v_fma_f32 v54, v84, v120, v54
	v_fma_f32 v55, v84, v121, v55
	v_fma_f32 v76, v38, v92, v54
	v_fma_f32 v77, v39, v92, v55
	v_mul_f32_e32 v38, v142, v68
	v_mul_f32_e32 v39, v142, v69
	v_fma_f32 v32, v32, v66, v50
	v_fma_f32 v33, v33, v66, v51
	v_mul_f32_e32 v50, v106, v140
	v_mul_f32_e32 v51, v107, v140
	v_fma_f32 v36, v36, v66, v38
	v_fma_f32 v37, v37, v66, v39
	v_mul_f32_e32 v38, v140, v114
	v_mul_f32_e32 v39, v140, v115
	v_mul_f32_e32 v32, v32, v0
	v_mul_f32_e32 v33, v33, v0
	v_fma_f32 v50, v84, v110, v50
	v_fma_f32 v51, v84, v111, v51
	v_mul_f32_e32 v36, v36, v0
	v_mul_f32_e32 v37, v37, v0
	v_fma_f32 v38, v84, v118, v38
	v_fma_f32 v39, v84, v119, v39
	v_fma_f32 v32, v32, v92, v50
	v_fma_f32 v33, v33, v92, v51
	global_load_dwordx4 v[50:53], v85, s[44:45]
	global_load_dwordx4 v[72:75], v85, s[44:45] offset:32
	v_fma_f32 v78, v36, v92, v38
	v_fma_f32 v79, v37, v92, v39
	v_mul_f32_e32 v36, v142, v64
	v_mul_f32_e32 v37, v142, v65
	v_fma_f32 v36, v40, v66, v36
	v_fma_f32 v37, v41, v66, v37
	v_mul_f32_e32 v40, v142, v62
	v_mul_f32_e32 v41, v142, v63
	v_fma_f32 v18, v18, v66, v40
	v_fma_f32 v19, v19, v66, v41
	s_waitcnt vmcnt(3)
	v_mul_f32_e32 v40, v132, v140
	v_mul_f32_e32 v41, v133, v140
	s_waitcnt vmcnt(2)
; DI void write_headnorm(const f32x16& o0, const f32x16& o1, const float* __restrict__ gh, u16* obuf, int tq, int colbase) {
;   const int h2 = (TIDX & 63) >> 5;
;   float ss = 0.f;
; #pragma unroll
;   for (int i = 0; i < 16; ++i) ss += o0[i] * o0[i] + o1[i] * o1[i];
;   ss += __shfl_xor(ss, 32);
;   const float rstd = rsqrtf(ss * (1.f / 64.f) + 1e-6f);
; #pragma unroll
;   for (int dt = 0; dt < 2; ++dt)
; #pragma unroll
;     for (int g = 0; g < 4; ++g) {
;       const int d = dt * 32 + 8 * g + 4 * h2;
;       f32x4 gg = *reinterpret_cast<const f32x4*>(gh + d);
;       float v0 = (dt ? o1[4 * g + 0] : o0[4 * g + 0]) * rstd * gg[0];
;       float v1 = (dt ? o1[4 * g + 1] : o0[4 * g + 1]) * rstd * gg[1];
;       float v2 = (dt ? o1[4 * g + 2] : o0[4 * g + 2]) * rstd * gg[2];
;       float v3 = (dt ? o1[4 * g + 3] : o0[4 * g + 3]) * rstd * gg[3];
;       u32x2 pk = {pack2(v0, v1), pack2(v2, v3)};
;       *reinterpret_cast<u32x2*>(obuf + (size_t)tq * DM + colbase + d) = pk;
;     }
; }
; DI void nsa_group(const u16* R, const u16* T, const float* Oc, const float* Ow, const u32* selm, const float* bg, const float* gh, u16* obuf, int qtile, char* lds) {
;     ...
; #pragma unroll
;       for (int j = 0; j < 4; ++j) {
;         a0[4 * g + j] = gc * a[j] + gw * wa[j] + gs * st.o0[4 * g + j];
;         a1[4 * g + j] = gc * b[j] + gw * wb[j] + gs * st.o1[4 * g + j];
;       }
;     }
;     write_headnorm(a0, a1, gh + hh * 64, obuf, tq, hh * 64);
	v_mul_f32_e32 v58, v140, v136
	v_mul_f32_e32 v59, v140, v137
	v_mul_f32_e32 v18, v18, v0
	v_mul_f32_e32 v19, v19, v0
	v_fma_f32 v40, v84, v124, v40
	v_fma_f32 v41, v84, v125, v41
	v_fma_f32 v58, v84, v128, v58
	v_fma_f32 v59, v84, v129, v59
	v_mul_f32_e32 v38, v140, v48
	v_mul_f32_e32 v39, v140, v49
	v_fma_f32 v40, v18, v92, v40
	v_fma_f32 v41, v19, v92, v41
	v_fma_f32 v58, v22, v92, v58
	v_fma_f32 v59, v23, v92, v59
	v_mul_f32_e32 v36, v36, v0
	v_mul_f32_e32 v37, v37, v0
	v_fma_f32 v6, v84, v6, v38
	v_fma_f32 v7, v84, v7, v39
	v_mul_f32_e32 v18, v40, v40
	v_mul_f32_e32 v19, v41, v41
	v_mul_f32_e32 v22, v58, v58
	v_mul_f32_e32 v23, v59, v59
	v_fma_f32 v6, v36, v92, v6
	v_fma_f32 v7, v37, v92, v7
	global_load_dwordx4 v[36:39], v85, s[44:45] offset:64
	global_load_dwordx4 v[68:71], v85, s[44:45] offset:96
	v_fma_f32 v48, v34, v34, v18
	v_fma_f32 v49, v35, v35, v19
	v_mul_f32_e32 v18, v60, v142
	v_mul_f32_e32 v19, v61, v142
	v_fma_f32 v80, v76, v76, v22
	v_fma_f32 v81, v77, v77, v23
	v_mul_f32_e32 v22, v142, v56
	v_mul_f32_e32 v23, v142, v57
	v_fma_f32 v16, v16, v66, v18
	v_fma_f32 v17, v17, v66, v19
	v_mul_f32_e32 v18, v130, v140
	v_mul_f32_e32 v19, v131, v140
	v_fma_f32 v20, v20, v66, v22
	v_fma_f32 v21, v21, v66, v23
	v_mul_f32_e32 v22, v140, v134
	v_mul_f32_e32 v23, v140, v135
	v_mul_f32_e32 v16, v16, v0
	v_mul_f32_e32 v17, v17, v0
	v_fma_f32 v18, v84, v122, v18
	v_fma_f32 v19, v84, v123, v19
	v_mul_f32_e32 v20, v20, v0
	v_mul_f32_e32 v21, v21, v0
	v_fma_f32 v22, v84, v126, v22
	v_fma_f32 v23, v84, v127, v23
	v_fma_f32 v64, v16, v92, v18
	v_fma_f32 v65, v17, v92, v19
	v_fma_f32 v82, v20, v92, v22
	v_fma_f32 v83, v21, v92, v23
	v_mul_f32_e32 v16, v64, v64
	v_mul_f32_e32 v17, v65, v65
	v_mul_f32_e32 v20, v82, v82
	v_mul_f32_e32 v21, v83, v83
	v_fma_f32 v54, v32, v32, v16
	v_fma_f32 v55, v33, v33, v17
	global_load_dwordx4 v[16:19], v85, s[44:45] offset:128
	global_load_dwordx4 v[60:63], v85, s[44:45] offset:160
	v_fma_f32 v86, v78, v78, v20
	v_fma_f32 v87, v79, v79, v21
	global_load_dwordx4 v[20:23], v85, s[44:45] offset:192
	v_add_f32_e32 v0, v54, v55
	global_load_dwordx4 v[54:57], v85, s[44:45] offset:224
	v_add_f32_e32 v0, v48, v0
	v_add_f32_e32 v0, v49, v0
	v_add_f32_e32 v0, v86, v0
	v_add_f32_e32 v0, v87, v0
	v_add_f32_e32 v0, v80, v0
	v_fma_f32 v10, v6, v6, v10
	v_fma_f32 v11, v7, v7, v11
	v_add_f32_e32 v0, v81, v0
	v_add_f32_e32 v0, v10, v0
	v_add_f32_e32 v0, v11, v0
	v_add_f32_e32 v0, v42, v0
	v_add_f32_e32 v0, v43, v0
	v_add_f32_e32 v0, v44, v0
	v_add_f32_e32 v0, v45, v0
	v_add_f32_e32 v0, v46, v0
	v_add_f32_e32 v0, v47, v0
	ds_bpermute_b32 v14, v138, v0
	v_lshlrev_b64 v[10:11], 11, v[88:89]
	v_lshl_add_u64 v[10:11], s[10:11], 0, v[10:11]
	v_lshl_add_u64 v[10:11], v[10:11], 0, s[2:3]
	s_waitcnt lgkmcnt(0)
	v_add_f32_e32 v0, v0, v14
	v_fmamk_f32 v0, v0, 0x3c800000, v158
	v_mul_f32_e32 v14, 0x4b800000, v0
	v_cmp_gt_f32_e32 vcc, s33, v0
	s_nop 1
	v_cndmask_b32_e32 v0, v0, v14, vcc
	v_rsq_f32_e32 v14, v0
	v_lshlrev_b32_e32 v0, 1, v67
	v_lshl_add_u64 v[10:11], v[10:11], 0, v[0:1]
	v_mul_f32_e32 v0, 0x45800000, v14
	v_cndmask_b32_e32 v0, v14, v0, vcc
	v_mul_f32_e32 v14, v32, v0
	v_mul_f32_e32 v15, v33, v0
	v_mul_f32_e32 v24, v34, v0
	v_mul_f32_e32 v25, v35, v0
	v_mul_f32_e32 v6, v6, v0
	v_mul_f32_e32 v7, v7, v0
	v_mul_f32_e32 v2, v2, v0
	v_mul_f32_e32 v3, v3, v0
	s_waitcnt vmcnt(7)
	v_mul_f32_e32 v14, v50, v14
	v_mul_f32_e32 v15, v51, v15
	v_mul_f32_e32 v24, v52, v24
	v_mul_f32_e32 v25, v53, v25
	v_cvt_pk_bf16_f32 v14, v14, v15
	v_cvt_pk_bf16_f32 v15, v24, v25
	global_store_dwordx2 v[10:11], v[14:15], off
	v_mul_f32_e32 v14, v78, v0
	v_mul_f32_e32 v15, v79, v0
	v_mul_f32_e32 v24, v76, v0
	v_mul_f32_e32 v25, v77, v0
	s_waitcnt vmcnt(7)
	v_mul_f32_e32 v14, v72, v14
	v_mul_f32_e32 v15, v73, v15
	v_mul_f32_e32 v24, v74, v24
	v_mul_f32_e32 v25, v75, v25
	v_cvt_pk_bf16_f32 v14, v14, v15
	v_cvt_pk_bf16_f32 v15, v24, v25
	global_store_dwordx2 v[10:11], v[14:15], off offset:16
	v_mul_f32_e32 v14, v26, v0
	v_mul_f32_e32 v15, v27, v0
	v_mul_f32_e32 v4, v4, v0
	v_mul_f32_e32 v5, v5, v0
	s_waitcnt vmcnt(7)
	v_mul_f32_e32 v6, v36, v6
	v_mul_f32_e32 v7, v37, v7
	v_mul_f32_e32 v14, v38, v14
	v_mul_f32_e32 v15, v39, v15
	v_cvt_pk_bf16_f32 v6, v6, v7
	v_cvt_pk_bf16_f32 v7, v14, v15
	global_store_dwordx2 v[10:11], v[6:7], off offset:32
	v_mul_f32_e32 v6, v12, v0
	v_mul_f32_e32 v7, v13, v0
	v_mul_f32_e32 v12, v30, v0
	v_mul_f32_e32 v13, v31, v0
	s_waitcnt vmcnt(7)
	v_mul_f32_e32 v6, v68, v6
	v_mul_f32_e32 v7, v69, v7
	v_mul_f32_e32 v12, v70, v12
	v_mul_f32_e32 v13, v71, v13
	v_cvt_pk_bf16_f32 v6, v6, v7
	v_cvt_pk_bf16_f32 v7, v12, v13
	global_store_dwordx2 v[10:11], v[6:7], off offset:48
	v_mul_f32_e32 v6, v64, v0
	v_mul_f32_e32 v7, v65, v0
	v_mul_f32_e32 v12, v40, v0
	v_mul_f32_e32 v13, v41, v0
	s_waitcnt vmcnt(7)
	v_mul_f32_e32 v6, v16, v6
	v_mul_f32_e32 v7, v17, v7
	v_mul_f32_e32 v12, v18, v12
	v_mul_f32_e32 v13, v19, v13
	v_cvt_pk_bf16_f32 v6, v6, v7
	s_waitcnt vmcnt(5)
	v_mul_f32_e32 v2, v20, v2
	v_mul_f32_e32 v3, v21, v3
	v_mul_f32_e32 v4, v22, v4
	v_mul_f32_e32 v5, v23, v5
	v_cvt_pk_bf16_f32 v7, v12, v13
	v_cvt_pk_bf16_f32 v2, v2, v3
	v_cvt_pk_bf16_f32 v3, v4, v5
	global_store_dwordx2 v[10:11], v[6:7], off offset:64
	v_mul_f32_e32 v6, v82, v0
	v_mul_f32_e32 v7, v83, v0
	v_mul_f32_e32 v12, v58, v0
	v_mul_f32_e32 v13, v59, v0
	global_store_dwordx2 v[10:11], v[2:3], off offset:96
	v_mul_f32_e32 v2, v8, v0
	v_mul_f32_e32 v3, v9, v0
	v_mul_f32_e32 v4, v28, v0
	v_mul_f32_e32 v5, v29, v0
	v_mul_f32_e32 v6, v60, v6
	v_mul_f32_e32 v7, v61, v7
	v_mul_f32_e32 v12, v62, v12
	v_mul_f32_e32 v13, v63, v13
	s_waitcnt vmcnt(6)
	v_mul_f32_e32 v2, v54, v2
	v_mul_f32_e32 v3, v55, v3
	v_mul_f32_e32 v4, v56, v4
	v_mul_f32_e32 v5, v57, v5
	v_cvt_pk_bf16_f32 v6, v6, v7
	v_cvt_pk_bf16_f32 v7, v12, v13
	v_cvt_pk_bf16_f32 v2, v2, v3
	v_cvt_pk_bf16_f32 v3, v4, v5
	global_store_dwordx2 v[10:11], v[6:7], off offset:80
	global_store_dwordx2 v[10:11], v[2:3], off offset:112
	s_branch .LBB0_865

; #define NEG_INF (-__builtin_inff())
; DI int pi_row(int r) { return (r & ~12) | ((r & 4) << 1) | ((r & 8) >> 1); }
; DI void softmax_step(float (&sc)[16], AState& st, const KV& kv) {
;   float mx = NEG_INF;
; #pragma unroll
;   for (int i = 0; i < 16; ++i) mx = fmaxf(mx, sc[i]);
;   mx = fmaxf(mx, __shfl_xor(mx, 32));
;   const float mnew = fmaxf(st.m, mx);
;   const float meff = (mnew == NEG_INF) ? 0.f : mnew;
;   const float alpha = __expf(st.m - meff);
;   float rs = 0.f;
; #pragma unroll
;   for (int i = 0; i < 16; ++i) { sc[i] = __expf(sc[i] - meff); rs += sc[i]; }
;   st.l = st.l * alpha + rs;
;   st.m = mnew;
;   if (__any(alpha != 1.f)) {
; #pragma unroll
;     for (int i = 0; i < 16; ++i) { st.o0[i] *= alpha; st.o1[i] *= alpha; }
; DI void nsa_group(const u16* R, const u16* T, const float* Oc, const float* Ow, const u32* selm, const float* bg, const float* gh, u16* obuf, int qtile, char* lds) {
;     ...
;       if (myh) {
;         const char* b = lds + buf * (2 * NG_TB) + part * NG_TB;
;         const u16* sK = reinterpret_cast<const u16*>(b);
;         const u16* sV = reinterpret_cast<const u16*>(b + 32 * FG_KROW * 2);
;         KV kv;
;         const int prow = pi_row(r);
; #pragma unroll
;         for (int ks = 0; ks < 4; ++ks) kv.k[ks] = ld16(sK + prow * FG_KROW + ks * 16 + h2 * 8);
; #pragma unroll
;         for (int dt = 0; dt < 2; ++dt)
; #pragma unroll
;           for (int a = 0; a < 2; ++a) kv.v[dt * 2 + a] = ld16(sV + (dt * 32 + r) * FG_VROW + a * 16 + h2 * 8);
;         f32x16 s = qk_tile(kv, q);
;         float sc[16];
;         const int nb = myn + 8 * h2;
; #pragma unroll
;         for (int i = 0; i < 16; ++i) {
;           const int n = nb + (i & 7) + 16 * (i >> 3);
;           const int dist = tq - n;
;           sc[i] = (dist >= 0 && mylb) ? s[i] + nslope * (float)dist : NEG_INF;
;         }
;         softmax_step(sc, st, kv);
.LBB0_1189:
	s_or_b64 exec, exec, s[54:55]
	s_or_b64 s[52:53], s[46:47], s[52:53]
	s_andn2_b64 vcc, exec, s[52:53]
	s_cbranch_vccnz .LBB0_1193
	s_and_b64 s[52:53], s[46:47], exec
	s_mul_i32 s14, s11, 0x4c00
	s_cselect_b32 s12, s12, s91
	s_add_i32 s14, s86, s14
	v_add_u32_e32 v0, s14, v111
	v_add_u32_e32 v10, v0, v110
	ds_read_b128 v[2:5], v10
	ds_read_b128 v[6:9], v10 offset:32
	v_cndmask_b32_e64 v11, 0, 1, s[48:49]
	v_cndmask_b32_e64 v12, 0, 1, s[50:51]
	s_waitcnt vmcnt(3) lgkmcnt(1)
	v_mfma_f32_32x32x16_bf16 v[48:63], v[2:5], v[64:67], 0
	v_cndmask_b32_e64 v2, v12, v11, s[46:47]
	v_and_b32_e32 v2, 1, v2
	v_cmp_eq_u32_e32 vcc, 1, v2
	ds_read_b128 v[2:5], v10 offset:64
	v_add_u32_e32 v11, s12, v112
	v_sub_u32_e32 v12, v88, v11
	v_xad_u32 v13, v11, -1, v88
	s_waitcnt vmcnt(2) lgkmcnt(1)
	v_mfma_f32_32x32x16_bf16 v[48:63], v[6:9], v[68:71], v[48:63]
	ds_read_b128 v[6:9], v10 offset:96
	v_cvt_f32_u32_e32 v10, v12
	v_sub_u32_e32 v14, v114, v11
	v_sub_u32_e32 v15, v115, v11
	v_cmp_lt_i32_e64 s[48:49], -1, v12
	v_cmp_lt_i32_e64 s[50:51], -1, v13
	s_and_b64 s[48:49], s[48:49], vcc
	s_waitcnt vmcnt(1) lgkmcnt(1)
	v_mfma_f32_32x32x16_bf16 v[48:63], v[2:5], v[72:75], v[48:63]
	v_cvt_f32_u32_e32 v2, v13
	v_cvt_f32_u32_e32 v3, v14
	v_cvt_f32_u32_e32 v4, v15
	v_sub_u32_e32 v129, v116, v11
	v_cmp_lt_i32_e64 s[52:53], -1, v14
	v_cmp_lt_i32_e64 s[54:55], -1, v15
	v_cvt_f32_u32_e32 v5, v129
	s_waitcnt vmcnt(0) lgkmcnt(0)
	v_mfma_f32_32x32x16_bf16 v[48:63], v[6:9], v[76:79], v[48:63]
	v_cmp_lt_i32_e64 s[56:57], -1, v129
	s_nop 10
	v_fma_f32 v6, -v109, v10, v48
	v_fma_f32 v2, -v109, v2, v49
	v_cndmask_b32_e64 v130, v184, v6, s[48:49]
	s_and_b64 s[48:49], s[50:51], vcc
	v_fma_f32 v3, -v109, v3, v50
	v_cndmask_b32_e64 v15, v184, v2, s[48:49]
	s_and_b64 s[48:49], s[52:53], vcc
	v_fma_f32 v4, -v109, v4, v51
	v_cndmask_b32_e64 v14, v184, v3, s[48:49]
	s_and_b64 s[48:49], s[54:55], vcc
	v_sub_u32_e32 v3, v117, v11
	v_cndmask_b32_e64 v131, v184, v4, s[48:49]
	v_cvt_f32_u32_e32 v4, v3
	v_fma_f32 v2, -v109, v5, v52
	s_and_b64 s[48:49], s[56:57], vcc
	v_cndmask_b32_e64 v52, v184, v2, s[48:49]
	v_cmp_lt_i32_e64 s[48:49], -1, v3
	v_sub_u32_e32 v3, v118, v11
	v_fma_f32 v2, -v109, v4, v53
	v_cvt_f32_u32_e32 v4, v3
	s_and_b64 s[48:49], s[48:49], vcc
	v_cndmask_b32_e64 v53, v184, v2, s[48:49]
	v_cmp_lt_i32_e64 s[48:49], -1, v3
	v_sub_u32_e32 v3, v119, v11
	v_fma_f32 v2, -v109, v4, v54
	v_cvt_f32_u32_e32 v4, v3
	s_and_b64 s[48:49], s[48:49], vcc
	v_cndmask_b32_e64 v54, v184, v2, s[48:49]
	v_cmp_lt_i32_e64 s[48:49], -1, v3
	v_sub_u32_e32 v3, v120, v11
	v_fma_f32 v2, -v109, v4, v55
	v_cvt_f32_u32_e32 v4, v3
	s_and_b64 s[48:49], s[48:49], vcc
	v_cndmask_b32_e64 v55, v184, v2, s[48:49]
	v_cmp_lt_i32_e64 s[48:49], -1, v3
	v_sub_u32_e32 v3, v121, v11
	v_fma_f32 v2, -v109, v4, v56
	v_cvt_f32_u32_e32 v4, v3
	s_and_b64 s[48:49], s[48:49], vcc
	v_cndmask_b32_e64 v56, v184, v2, s[48:49]
	v_cmp_lt_i32_e64 s[48:49], -1, v3
	v_sub_u32_e32 v3, v122, v11
	v_fma_f32 v2, -v109, v4, v57
	v_cvt_f32_u32_e32 v4, v3
	s_and_b64 s[48:49], s[48:49], vcc
	v_cndmask_b32_e64 v57, v184, v2, s[48:49]
	v_cmp_lt_i32_e64 s[48:49], -1, v3
	v_sub_u32_e32 v3, v123, v11
	v_fma_f32 v2, -v109, v4, v58
	v_cvt_f32_u32_e32 v4, v3
	s_and_b64 s[48:49], s[48:49], vcc
	v_cndmask_b32_e64 v132, v184, v2, s[48:49]
	v_cmp_lt_i32_e64 s[48:49], -1, v3
	v_sub_u32_e32 v3, v124, v11
	v_fma_f32 v2, -v109, v4, v59
	v_cvt_f32_u32_e32 v4, v3
	s_and_b64 s[48:49], s[48:49], vcc
	v_cndmask_b32_e64 v59, v184, v2, s[48:49]
	v_cmp_lt_i32_e64 s[48:49], -1, v3
	v_sub_u32_e32 v3, v125, v11
	v_fma_f32 v2, -v109, v4, v60
	v_cvt_f32_u32_e32 v4, v3
	s_and_b64 s[48:49], s[48:49], vcc
	v_cndmask_b32_e64 v60, v184, v2, s[48:49]
	v_cmp_lt_i32_e64 s[48:49], -1, v3
	v_sub_u32_e32 v3, v126, v11
	v_fma_f32 v2, -v109, v4, v61
	v_cvt_f32_u32_e32 v4, v3
	s_and_b64 s[48:49], s[48:49], vcc
	v_cndmask_b32_e64 v133, v184, v2, s[48:49]
	v_cmp_lt_i32_e64 s[48:49], -1, v3
	v_sub_u32_e32 v3, v127, v11
	v_fma_f32 v2, -v109, v4, v62
	v_cvt_f32_u32_e32 v4, v3
	s_and_b64 s[48:49], s[48:49], vcc
	v_cndmask_b32_e64 v62, v184, v2, s[48:49]
	v_cmp_lt_i32_e64 s[48:49], -1, v3
	v_fma_f32 v2, -v109, v4, v63
	s_and_b64 vcc, s[48:49], vcc
	v_cndmask_b32_e32 v58, v184, v2, vcc
	v_max3_f32 v2, v130, s35, v15
	v_max3_f32 v2, v2, v14, v131
	v_max3_f32 v2, v2, v52, v53
	v_max3_f32 v2, v2, v54, v55
	v_max3_f32 v2, v2, v56, v57
	v_max3_f32 v2, v2, v132, v59
	v_max3_f32 v2, v2, v60, v133
	v_max3_f32 v2, v2, v62, v58
	ds_bpermute_b32 v3, v138, v2
	v_add_u32_e32 v4, v0, v113
	ds_read_b128 v[48:51], v4 offset:4608
	ds_read_b128 v[10:13], v4 offset:4640
	s_waitcnt lgkmcnt(2)
	v_max3_f32 v129, v128, v2, v3
	v_cmp_neq_f32_e32 vcc, s35, v129
	ds_read_b128 v[6:9], v4 offset:7168
	ds_read_b128 v[2:5], v4 offset:7200
	v_cndmask_b32_e32 v61, 0, v129, vcc
	v_sub_f32_e32 v0, v128, v61
	v_mul_f32_e32 v0, 0x3fb8aa3b, v0
	v_exp_f32_e32 v0, v0
	s_nop 0
	v_cmp_neq_f32_e32 vcc, 1.0, v0
	s_cbranch_vccz .LBB0_1192
	v_mul_f32_e32 v46, v46, v0
	v_mul_f32_e32 v47, v47, v0
	v_mul_f32_e32 v44, v44, v0
	v_mul_f32_e32 v45, v45, v0
	v_mul_f32_e32 v42, v42, v0
	v_mul_f32_e32 v43, v43, v0
	v_mul_f32_e32 v40, v40, v0
	v_mul_f32_e32 v41, v41, v0
	v_mul_f32_e32 v38, v38, v0
	v_mul_f32_e32 v39, v39, v0
	v_mul_f32_e32 v36, v36, v0
	v_mul_f32_e32 v37, v37, v0
	v_mul_f32_e32 v34, v34, v0
	v_mul_f32_e32 v35, v35, v0
	v_mul_f32_e32 v32, v32, v0
	v_mul_f32_e32 v33, v33, v0
	v_mul_f32_e32 v30, v30, v0
	v_mul_f32_e32 v31, v31, v0
	v_mul_f32_e32 v28, v28, v0
	v_mul_f32_e32 v29, v29, v0
	v_mul_f32_e32 v26, v26, v0
	v_mul_f32_e32 v27, v27, v0
	v_mul_f32_e32 v24, v24, v0
	v_mul_f32_e32 v25, v25, v0
	v_mul_f32_e32 v22, v22, v0
	v_mul_f32_e32 v23, v23, v0
	v_mul_f32_e32 v20, v20, v0
	v_mul_f32_e32 v21, v21, v0
	v_mul_f32_e32 v18, v18, v0
	v_mul_f32_e32 v19, v19, v0
	v_mul_f32_e32 v16, v16, v0
	v_mul_f32_e32 v17, v17, v0
